# 256x256 GEMM K-loops (P1,P6,P8) hand-written: fragment reads pipelined across the barrier, LDS-DMA pieces spread one per MFMA group
# speedup vs baseline: 1.0285x; 1.0165x over previous
; template <class Epi>
; DI void gemm_tile256(const u16* __restrict__ Ag, long lda, const u16* __restrict__ Bg, long ldb, int nk, char* shm, Epi&& epi) {
;   const int tid = RTID, wid = tid >> 6, lane = tid & 63, wr = wid >> 2, wc = wid & 3, fr = lane & 15, fq = lane >> 4;
;   f32x4 acc[8][4];
; #pragma unroll
;   for (int m = 0; m < 8; ++m)
; #pragma unroll
;     for (int n = 0; n < 4; ++n) acc[m][n] = f32x4{0.f, 0.f, 0.f, 0.f};
;   const int q0 = tid, q1 = 512 + tid;
;   const int r0 = q0 >> 2, r1 = q1 >> 2, c0 = (q0 & 3) ^ ((r0 >> 2) & 3), c1 = (q1 & 3) ^ ((r1 >> 2) & 3);
;   const u16* a0 = Ag + (long)r0 * lda + c0 * 8; const u16* a1 = Ag + (long)r1 * lda + c1 * 8;
;   const u16* b0 = Bg + (long)r0 * ldb + c0 * 8; const u16* b1 = Bg + (long)r1 * ldb + c1 * 8;
;   auto stage = [&](int j) {
;     char* SA = shm + (j & 3) * 32768; char* SB = SA + 16384;
;     __builtin_amdgcn_global_load_lds((const unsigned*)(a0 + j * 32), (__attribute__((address_space(3))) unsigned*)(SA + q0 * 16), 16, 0, 0);
;     __builtin_amdgcn_global_load_lds((const unsigned*)(a1 + j * 32), (__attribute__((address_space(3))) unsigned*)(SA + q1 * 16), 16, 0, 0);
;     __builtin_amdgcn_global_load_lds((const unsigned*)(b0 + j * 32), (__attribute__((address_space(3))) unsigned*)(SB + q0 * 16), 16, 0, 0);
;     __builtin_amdgcn_global_load_lds((const unsigned*)(b1 + j * 32), (__attribute__((address_space(3))) unsigned*)(SB + q1 * 16), 16, 0, 0);
;   };
;   __syncthreads();
;   stage(0);
;   if (nk > 1) stage(1);
;   if (nk > 2) stage(2);
;   for (int i = 0; i < nk; ++i) {
;     if (i + 2 < nk) asm volatile("s_waitcnt vmcnt(8)" ::: "memory");
;     else if (i + 1 < nk) asm volatile("s_waitcnt vmcnt(4)" ::: "memory");
;     else asm volatile("s_waitcnt vmcnt(0)" ::: "memory");
;     __builtin_amdgcn_s_barrier();
;     const char* SA = shm + (i & 3) * 32768; const char* SB = SA + 16384;
.LBB0_107:
	v_lshl_add_u64 v[176:177], v[138:139], 0, 64
	v_lshl_add_u64 v[178:179], v[140:141], 0, 64
	v_lshl_add_u64 v[180:181], v[138:139], 0, s[0:1]
	v_lshl_add_u64 v[182:183], v[140:141], 0, s[0:1]
	s_lshl_b32 s30, s27, 8
	s_ashr_i32 s29, s28, 31
	s_ashr_i32 s31, s30, 31
	s_lshl_b64 s[6:7], s[28:29], 11
	s_lshl_b64 s[4:5], s[30:31], 11
	s_add_u32 s4, s54, s4
	s_addc_u32 s5, s55, s5
	v_add_u32_e32 v6, 0, v209
	v_lshl_add_u64 v[0:1], s[4:5], 0, v[132:133]
	v_lshl_add_u64 v[2:3], s[4:5], 0, v[136:137]
	v_readfirstlane_b32 s4, v6
	v_add_u32_e32 v7, 0, v131
	v_lshl_add_u64 v[0:1], v[0:1], 0, v[134:135]
	s_mov_b32 m0, s4
	v_readfirstlane_b32 s4, v7
	v_add_u32_e32 v4, 0x4000, v6
	v_lshl_add_u64 v[2:3], v[2:3], 0, v[134:135]
	s_barrier
	global_load_lds_dwordx4 v[0:1], off
	s_mov_b32 m0, s4
	v_readfirstlane_b32 s4, v4
	v_add_u32_e32 v4, 0x4000, v7
	global_load_lds_dwordx4 v[2:3], off
	s_mov_b32 m0, s4
	v_readfirstlane_b32 s4, v4
	v_add_u32_e32 v8, 0x8000, v6
	global_load_lds_dwordx4 v[138:139], off
	s_mov_b32 m0, s4
	v_readfirstlane_b32 s4, v8
	v_add_u32_e32 v8, 0x8000, v7
	global_load_lds_dwordx4 v[140:141], off
	v_lshl_add_u64 v[4:5], v[0:1], 0, 64
	s_mov_b32 m0, s4
	v_readfirstlane_b32 s4, v8
	global_load_lds_dwordx4 v[4:5], off
	v_lshl_add_u64 v[4:5], v[2:3], 0, 64
	s_mov_b32 m0, s4
	v_lshl_add_u64 v[0:1], v[0:1], 0, s[0:1]
	global_load_lds_dwordx4 v[4:5], off
	v_add_u32_e32 v4, 0xc000, v6
	s_mov_b32 s8, 0x18000
	v_readfirstlane_b32 s4, v4
	v_add_u32_e32 v4, 0xc000, v7
	s_mov_b32 m0, s4
	v_readfirstlane_b32 s4, v4
	v_add_u32_e32 v4, s2, v209
	global_load_lds_dwordx4 v[176:177], off
	s_mov_b32 m0, s4
	v_readfirstlane_b32 s4, v4
	global_load_lds_dwordx4 v[178:179], off
	s_mov_b32 m0, s4
	v_mov_b32_e32 v4, 0
	global_load_lds_dwordx4 v[0:1], off
	v_lshl_add_u64 v[0:1], v[2:3], 0, s[0:1]
	v_add_u32_e32 v2, s2, v131
	v_mov_b32_e32 v3, v135
	v_readfirstlane_b32 s4, v2
	s_mov_b32 m0, s4
	v_mov_b32_e32 v2, v135
	global_load_lds_dwordx4 v[0:1], off
	v_add_u32_e32 v0, s15, v209
	v_mov_b32_e32 v1, v135
	v_readfirstlane_b32 s4, v0
	v_add_u32_e32 v0, s15, v131
	s_mov_b32 m0, s4
	v_readfirstlane_b32 s4, v0
	global_load_lds_dwordx4 v[180:181], off
	s_mov_b32 m0, s4
	s_mov_b64 s[4:5], 0
	global_load_lds_dwordx4 v[182:183], off
	v_mov_b32_e32 v0, 0
	v_mov_b32_e32 v5, v135
	v_mov_b32_e32 v6, v135
	v_mov_b32_e32 v7, v135
	v_mov_b32_e32 v8, 0
	v_mov_b32_e32 v9, v135
	v_mov_b32_e32 v10, v135
	v_mov_b32_e32 v11, v135
	v_mov_b32_e32 v12, 0
	v_mov_b32_e32 v13, v135
	v_mov_b32_e32 v14, v135
	v_mov_b32_e32 v15, v135
	v_mov_b32_e32 v16, 0
	v_mov_b32_e32 v17, v135
	v_mov_b32_e32 v18, v135
	v_mov_b32_e32 v19, v135
	v_mov_b32_e32 v20, 0
	v_mov_b32_e32 v21, v135
	v_mov_b32_e32 v22, v135
	v_mov_b32_e32 v23, v135
	v_mov_b32_e32 v24, 0
	v_mov_b32_e32 v25, v135
	v_mov_b32_e32 v26, v135
	v_mov_b32_e32 v27, v135
	v_mov_b32_e32 v28, 0
	v_mov_b32_e32 v29, v135
	v_mov_b32_e32 v30, v135
	v_mov_b32_e32 v31, v135
	v_mov_b32_e32 v32, 0
	v_mov_b32_e32 v33, v135
	v_mov_b32_e32 v34, v135
	v_mov_b32_e32 v35, v135
	v_mov_b32_e32 v36, 0
	v_mov_b32_e32 v37, v135
	v_mov_b32_e32 v38, v135
	v_mov_b32_e32 v39, v135
	v_mov_b32_e32 v40, 0
	v_mov_b32_e32 v41, v135
	v_mov_b32_e32 v42, v135
	v_mov_b32_e32 v43, v135
	v_mov_b32_e32 v44, 0
	v_mov_b32_e32 v45, v135
	v_mov_b32_e32 v46, v135
	v_mov_b32_e32 v47, v135
	v_mov_b32_e32 v48, 0
	v_mov_b32_e32 v49, v135
	v_mov_b32_e32 v50, v135
	v_mov_b32_e32 v51, v135
	v_mov_b32_e32 v52, 0
	v_mov_b32_e32 v53, v135
	v_mov_b32_e32 v54, v135
	v_mov_b32_e32 v55, v135
	v_mov_b32_e32 v56, 0
	v_mov_b32_e32 v57, v135
	v_mov_b32_e32 v58, v135
	v_mov_b32_e32 v59, v135
	v_mov_b32_e32 v60, 0
	v_mov_b32_e32 v61, v135
	v_mov_b32_e32 v62, v135
	v_mov_b32_e32 v63, v135
	v_mov_b32_e32 v64, 0
	v_mov_b32_e32 v65, v135
	v_mov_b32_e32 v66, v135
	v_mov_b32_e32 v67, v135
	v_mov_b32_e32 v68, 0
	v_mov_b32_e32 v69, v135
	v_mov_b32_e32 v70, v135
	v_mov_b32_e32 v71, v135
	v_mov_b32_e32 v72, 0
	v_mov_b32_e32 v73, v135
	v_mov_b32_e32 v74, v135
	v_mov_b32_e32 v75, v135
	v_mov_b32_e32 v76, 0
	v_mov_b32_e32 v77, v135
	v_mov_b32_e32 v78, v135
	v_mov_b32_e32 v79, v135
	v_mov_b32_e32 v80, 0
	v_mov_b32_e32 v81, v135
	v_mov_b32_e32 v82, v135
	v_mov_b32_e32 v83, v135
	v_mov_b32_e32 v84, 0
	v_mov_b32_e32 v85, v135
	v_mov_b32_e32 v86, v135
	v_mov_b32_e32 v87, v135
	v_mov_b32_e32 v88, 0
	v_mov_b32_e32 v89, v135
	v_mov_b32_e32 v90, v135
	v_mov_b32_e32 v91, v135
	v_mov_b32_e32 v92, 0
	v_mov_b32_e32 v93, v135
	v_mov_b32_e32 v94, v135
	v_mov_b32_e32 v95, v135
	v_mov_b32_e32 v96, 0
	v_mov_b32_e32 v97, v135
	v_mov_b32_e32 v98, v135
	v_mov_b32_e32 v99, v135
	v_mov_b32_e32 v100, 0
	v_mov_b32_e32 v101, v135
	v_mov_b32_e32 v102, v135
	v_mov_b32_e32 v103, v135
	v_mov_b32_e32 v104, 0
	v_mov_b32_e32 v105, v135
	v_mov_b32_e32 v106, v135
	v_mov_b32_e32 v107, v135
	v_mov_b32_e32 v108, 0
	v_mov_b32_e32 v109, v135
	v_mov_b32_e32 v110, v135
	v_mov_b32_e32 v111, v135
	v_mov_b32_e32 v112, 0
	v_mov_b32_e32 v113, v135
	v_mov_b32_e32 v114, v135
	v_mov_b32_e32 v115, v135
	v_mov_b32_e32 v116, 0
	v_mov_b32_e32 v117, v135
	v_mov_b32_e32 v118, v135
	v_mov_b32_e32 v119, v135
	v_mov_b32_e32 v120, 0
	v_mov_b32_e32 v121, v135
	v_mov_b32_e32 v122, v135
	v_mov_b32_e32 v123, v135
	v_mov_b32_e32 v124, 0
	v_mov_b32_e32 v125, v135
	v_mov_b32_e32 v126, v135
	v_mov_b32_e32 v127, v135
	v_lshl_add_u64 v[184:185], v[168:169], 0, s[6:7]
	v_lshl_add_u64 v[186:187], v[170:171], 0, s[6:7]
	v_readfirstlane_b32 s7, v209
	s_mov_b32 s8, 0
	s_mov_b64 s[4:5], 0
	s_waitcnt vmcnt(8)
	s_barrier
	v_add3_u32 v252, v205, v147, s8
	v_add3_u32 v215, v205, v151, s8
	s_nop 0
	ds_read_b128 v[216:219], v252 offset:16384
	ds_read_b128 v[220:223], v252 offset:17408
	ds_read_b128 v[232:235], v252 offset:18432
	ds_read_b128 v[236:239], v252 offset:19456
	ds_read_b128 v[224:227], v215
	ds_read_b128 v[228:231], v215 offset:1024
; template <class Epi>
; DI void gemm_tile256(const u16* __restrict__ Ag, long lda, const u16* __restrict__ Bg, long ldb, int nk, char* shm, Epi&& epi) {
;     ...
;   for (int i = 0; i < nk; ++i) {
;     if (i + 2 < nk) asm volatile("s_waitcnt vmcnt(8)" ::: "memory");
;     else if (i + 1 < nk) asm volatile("s_waitcnt vmcnt(4)" ::: "memory");
;     else asm volatile("s_waitcnt vmcnt(0)" ::: "memory");
;     __builtin_amdgcn_s_barrier();
;     const char* SA = shm + (i & 3) * 32768; const char* SB = SA + 16384;
;     bf16x8 At[8], Bt[4];
; #pragma unroll
;     for (int n = 0; n < 4; ++n) { const int rb = wc * 64 + n * 16 + fr; Bt[n] = *reinterpret_cast<const bf16x8*>(SB + rb * 64 + ((fq ^ ((rb >> 2) & 3)) * 16)); }
; #pragma unroll
;     for (int m = 0; m < 8; ++m) { const int ra = wr * 128 + m * 16 + fr; At[m] = *reinterpret_cast<const bf16x8*>(SA + ra * 64 + ((fq ^ ((ra >> 2) & 3)) * 16)); }
;     if (i + 3 < nk) stage(i + 3);
; #pragma unroll
;     for (int m = 0; m < 8; ++m)
; #pragma unroll
;       for (int n = 0; n < 4; ++n) acc[m][n] = __builtin_amdgcn_mfma_f32_16x16x32_bf16(Bt[n], At[m], acc[m][n], 0, 0, 0);
.Lgemm_p1_kloop:
	s_add_i32 s6, s8, 0x18000
	s_and_b32 s6, s6, 0x18000
	s_add_i32 s9, s6, s7
	ds_read_b128 v[180:183], v215 offset:2048
	ds_read_b128 v[210:213], v215 offset:3072
	s_waitcnt lgkmcnt(2)
	v_mfma_f32_16x16x32_bf16 v[124:127], v[216:219], v[224:227], v[124:127]
	v_lshl_add_u64 v[206:207], v[184:185], 0, s[4:5]
	v_mfma_f32_16x16x32_bf16 v[120:123], v[220:223], v[224:227], v[120:123]
	s_mov_b32 m0, s9
	v_mfma_f32_16x16x32_bf16 v[116:119], v[232:235], v[224:227], v[116:119]
	s_add_i32 s9, s9, 0x2000
	v_mfma_f32_16x16x32_bf16 v[112:115], v[236:239], v[224:227], v[112:115]
	global_load_lds_dwordx4 v[206:207], off
	v_mfma_f32_16x16x32_bf16 v[108:111], v[216:219], v[228:231], v[108:111]
	v_mfma_f32_16x16x32_bf16 v[104:107], v[220:223], v[228:231], v[104:107]
	v_mfma_f32_16x16x32_bf16 v[100:103], v[232:235], v[228:231], v[100:103]
	v_mfma_f32_16x16x32_bf16 v[96:99], v[236:239], v[228:231], v[96:99]
	ds_read_b128 v[224:227], v215 offset:4096
	ds_read_b128 v[228:231], v215 offset:5120
	s_waitcnt lgkmcnt(2)
	v_mfma_f32_16x16x32_bf16 v[92:95], v[216:219], v[180:183], v[92:95]
	v_lshl_add_u64 v[206:207], v[186:187], 0, s[4:5]
	v_mfma_f32_16x16x32_bf16 v[88:91], v[220:223], v[180:183], v[88:91]
	s_mov_b32 m0, s9
	v_mfma_f32_16x16x32_bf16 v[84:87], v[232:235], v[180:183], v[84:87]
	s_add_i32 s9, s9, 0x2000
	v_mfma_f32_16x16x32_bf16 v[80:83], v[236:239], v[180:183], v[80:83]
	global_load_lds_dwordx4 v[206:207], off
	v_mfma_f32_16x16x32_bf16 v[76:79], v[216:219], v[210:213], v[76:79]
	v_mfma_f32_16x16x32_bf16 v[72:75], v[220:223], v[210:213], v[72:75]
	v_mfma_f32_16x16x32_bf16 v[68:71], v[232:235], v[210:213], v[68:71]
	v_mfma_f32_16x16x32_bf16 v[64:67], v[236:239], v[210:213], v[64:67]
	ds_read_b128 v[180:183], v215 offset:6144
	ds_read_b128 v[210:213], v215 offset:7168
	s_waitcnt lgkmcnt(2)
	v_mfma_f32_16x16x32_bf16 v[60:63], v[216:219], v[224:227], v[60:63]
	v_lshl_add_u64 v[206:207], v[172:173], 0, s[4:5]
	v_mfma_f32_16x16x32_bf16 v[56:59], v[220:223], v[224:227], v[56:59]
	s_mov_b32 m0, s9
	v_mfma_f32_16x16x32_bf16 v[52:55], v[232:235], v[224:227], v[52:55]
	s_add_i32 s9, s9, 0x2000
	v_mfma_f32_16x16x32_bf16 v[48:51], v[236:239], v[224:227], v[48:51]
	global_load_lds_dwordx4 v[206:207], off
	v_mfma_f32_16x16x32_bf16 v[44:47], v[216:219], v[228:231], v[44:47]
	v_mfma_f32_16x16x32_bf16 v[40:43], v[220:223], v[228:231], v[40:43]
	v_mfma_f32_16x16x32_bf16 v[36:39], v[232:235], v[228:231], v[36:39]
	v_mfma_f32_16x16x32_bf16 v[32:35], v[236:239], v[228:231], v[32:35]
	s_add_i32 s8, s8, 0x8000
	s_and_b32 s8, s8, 0x18000
	s_waitcnt vmcnt(7) lgkmcnt(0)
	s_barrier
	v_add3_u32 v252, v205, v147, s8
	v_add3_u32 v215, v205, v151, s8
	s_nop 0
	ds_read_b128 v[240:243], v252 offset:16384
	ds_read_b128 v[244:247], v252 offset:17408
	ds_read_b128 v[248:251], v252 offset:18432
	ds_read_b128 v[176:179], v252 offset:19456
	ds_read_b128 v[224:227], v215
	ds_read_b128 v[228:231], v215 offset:1024
	v_mfma_f32_16x16x32_bf16 v[28:31], v[216:219], v[180:183], v[28:31]
	v_lshl_add_u64 v[206:207], v[174:175], 0, s[4:5]
	v_mfma_f32_16x16x32_bf16 v[24:27], v[220:223], v[180:183], v[24:27]
	s_mov_b32 m0, s9
	v_mfma_f32_16x16x32_bf16 v[20:23], v[232:235], v[180:183], v[20:23]
	s_add_i32 s9, s9, 0x2000
	v_mfma_f32_16x16x32_bf16 v[16:19], v[236:239], v[180:183], v[16:19]
	global_load_lds_dwordx4 v[206:207], off
	v_mfma_f32_16x16x32_bf16 v[12:15], v[216:219], v[210:213], v[12:15]
	s_add_u32 s4, s4, 64
	v_mfma_f32_16x16x32_bf16 v[8:11], v[220:223], v[210:213], v[8:11]
	s_addc_u32 s5, s5, 0
	v_mfma_f32_16x16x32_bf16 v[4:7], v[232:235], v[210:213], v[4:7]
	v_mfma_f32_16x16x32_bf16 v[0:3], v[236:239], v[210:213], v[0:3]
	s_add_i32 s6, s8, 0x18000
	s_and_b32 s6, s6, 0x18000
	s_add_i32 s9, s6, s7
	ds_read_b128 v[180:183], v215 offset:2048
	ds_read_b128 v[210:213], v215 offset:3072
	s_waitcnt lgkmcnt(2)
	v_mfma_f32_16x16x32_bf16 v[124:127], v[240:243], v[224:227], v[124:127]
	v_lshl_add_u64 v[206:207], v[184:185], 0, s[4:5]
	v_mfma_f32_16x16x32_bf16 v[120:123], v[244:247], v[224:227], v[120:123]
	s_mov_b32 m0, s9
	v_mfma_f32_16x16x32_bf16 v[116:119], v[248:251], v[224:227], v[116:119]
	s_add_i32 s9, s9, 0x2000
	v_mfma_f32_16x16x32_bf16 v[112:115], v[176:179], v[224:227], v[112:115]
	global_load_lds_dwordx4 v[206:207], off
	v_mfma_f32_16x16x32_bf16 v[108:111], v[240:243], v[228:231], v[108:111]
	v_mfma_f32_16x16x32_bf16 v[104:107], v[244:247], v[228:231], v[104:107]
	v_mfma_f32_16x16x32_bf16 v[100:103], v[248:251], v[228:231], v[100:103]
	v_mfma_f32_16x16x32_bf16 v[96:99], v[176:179], v[228:231], v[96:99]
	ds_read_b128 v[224:227], v215 offset:4096
	ds_read_b128 v[228:231], v215 offset:5120
	s_waitcnt lgkmcnt(2)
	v_mfma_f32_16x16x32_bf16 v[92:95], v[240:243], v[180:183], v[92:95]
	v_lshl_add_u64 v[206:207], v[186:187], 0, s[4:5]
	v_mfma_f32_16x16x32_bf16 v[88:91], v[244:247], v[180:183], v[88:91]
	s_mov_b32 m0, s9
	v_mfma_f32_16x16x32_bf16 v[84:87], v[248:251], v[180:183], v[84:87]
	s_add_i32 s9, s9, 0x2000
	v_mfma_f32_16x16x32_bf16 v[80:83], v[176:179], v[180:183], v[80:83]
	global_load_lds_dwordx4 v[206:207], off
	v_mfma_f32_16x16x32_bf16 v[76:79], v[240:243], v[210:213], v[76:79]
	v_mfma_f32_16x16x32_bf16 v[72:75], v[244:247], v[210:213], v[72:75]
	v_mfma_f32_16x16x32_bf16 v[68:71], v[248:251], v[210:213], v[68:71]
	v_mfma_f32_16x16x32_bf16 v[64:67], v[176:179], v[210:213], v[64:67]
	ds_read_b128 v[180:183], v215 offset:6144
	ds_read_b128 v[210:213], v215 offset:7168
	s_waitcnt lgkmcnt(2)
	v_mfma_f32_16x16x32_bf16 v[60:63], v[240:243], v[224:227], v[60:63]
	v_lshl_add_u64 v[206:207], v[172:173], 0, s[4:5]
	v_mfma_f32_16x16x32_bf16 v[56:59], v[244:247], v[224:227], v[56:59]
	s_mov_b32 m0, s9
	v_mfma_f32_16x16x32_bf16 v[52:55], v[248:251], v[224:227], v[52:55]
	s_add_i32 s9, s9, 0x2000
	v_mfma_f32_16x16x32_bf16 v[48:51], v[176:179], v[224:227], v[48:51]
	global_load_lds_dwordx4 v[206:207], off
	v_mfma_f32_16x16x32_bf16 v[44:47], v[240:243], v[228:231], v[44:47]
	v_mfma_f32_16x16x32_bf16 v[40:43], v[244:247], v[228:231], v[40:43]
	v_mfma_f32_16x16x32_bf16 v[36:39], v[248:251], v[228:231], v[36:39]
	v_mfma_f32_16x16x32_bf16 v[32:35], v[176:179], v[228:231], v[32:35]
	s_add_i32 s8, s8, 0x8000
	s_and_b32 s8, s8, 0x18000
	s_waitcnt vmcnt(7) lgkmcnt(0)
	s_barrier
; template <class Epi>
; DI void gemm_tile256(const u16* __restrict__ Ag, long lda, const u16* __restrict__ Bg, long ldb, int nk, char* shm, Epi&& epi) {
;     ...
;   for (int i = 0; i < nk; ++i) {
;     if (i + 2 < nk) asm volatile("s_waitcnt vmcnt(8)" ::: "memory");
;     else if (i + 1 < nk) asm volatile("s_waitcnt vmcnt(4)" ::: "memory");
;     else asm volatile("s_waitcnt vmcnt(0)" ::: "memory");
;     __builtin_amdgcn_s_barrier();
;     const char* SA = shm + (i & 3) * 32768; const char* SB = SA + 16384;
;     bf16x8 At[8], Bt[4];
; #pragma unroll
;     for (int n = 0; n < 4; ++n) { const int rb = wc * 64 + n * 16 + fr; Bt[n] = *reinterpret_cast<const bf16x8*>(SB + rb * 64 + ((fq ^ ((rb >> 2) & 3)) * 16)); }
; #pragma unroll
;     for (int m = 0; m < 8; ++m) { const int ra = wr * 128 + m * 16 + fr; At[m] = *reinterpret_cast<const bf16x8*>(SA + ra * 64 + ((fq ^ ((ra >> 2) & 3)) * 16)); }
;     if (i + 3 < nk) stage(i + 3);
; #pragma unroll
;     for (int m = 0; m < 8; ++m)
; #pragma unroll
;       for (int n = 0; n < 4; ++n) acc[m][n] = __builtin_amdgcn_mfma_f32_16x16x32_bf16(Bt[n], At[m], acc[m][n], 0, 0, 0);
	v_add3_u32 v252, v205, v147, s8
	v_add3_u32 v215, v205, v151, s8
	s_nop 0
	ds_read_b128 v[216:219], v252 offset:16384
	ds_read_b128 v[220:223], v252 offset:17408
	ds_read_b128 v[232:235], v252 offset:18432
	ds_read_b128 v[236:239], v252 offset:19456
	ds_read_b128 v[224:227], v215
	ds_read_b128 v[228:231], v215 offset:1024
	v_mfma_f32_16x16x32_bf16 v[28:31], v[240:243], v[180:183], v[28:31]
	v_lshl_add_u64 v[206:207], v[174:175], 0, s[4:5]
	v_mfma_f32_16x16x32_bf16 v[24:27], v[244:247], v[180:183], v[24:27]
	s_mov_b32 m0, s9
	v_mfma_f32_16x16x32_bf16 v[20:23], v[248:251], v[180:183], v[20:23]
	s_add_i32 s9, s9, 0x2000
	v_mfma_f32_16x16x32_bf16 v[16:19], v[176:179], v[180:183], v[16:19]
	global_load_lds_dwordx4 v[206:207], off
	v_mfma_f32_16x16x32_bf16 v[12:15], v[240:243], v[210:213], v[12:15]
	s_add_u32 s4, s4, 64
	v_mfma_f32_16x16x32_bf16 v[8:11], v[244:247], v[210:213], v[8:11]
	s_addc_u32 s5, s5, 0
	v_mfma_f32_16x16x32_bf16 v[4:7], v[248:251], v[210:213], v[4:7]
	v_mfma_f32_16x16x32_bf16 v[0:3], v[176:179], v[210:213], v[0:3]
	s_cmpk_lg_i32 s4, 0x700
	s_cbranch_scc1 .Lgemm_p1_kloop
	s_add_i32 s6, s8, 0x18000
	s_and_b32 s6, s6, 0x18000
	s_add_i32 s9, s6, s7
	ds_read_b128 v[180:183], v215 offset:2048
	ds_read_b128 v[210:213], v215 offset:3072
	s_waitcnt lgkmcnt(2)
	v_mfma_f32_16x16x32_bf16 v[124:127], v[216:219], v[224:227], v[124:127]
	v_lshl_add_u64 v[206:207], v[184:185], 0, s[4:5]
	v_mfma_f32_16x16x32_bf16 v[120:123], v[220:223], v[224:227], v[120:123]
	s_mov_b32 m0, s9
	v_mfma_f32_16x16x32_bf16 v[116:119], v[232:235], v[224:227], v[116:119]
	s_add_i32 s9, s9, 0x2000
	v_mfma_f32_16x16x32_bf16 v[112:115], v[236:239], v[224:227], v[112:115]
	global_load_lds_dwordx4 v[206:207], off
	v_mfma_f32_16x16x32_bf16 v[108:111], v[216:219], v[228:231], v[108:111]
	v_mfma_f32_16x16x32_bf16 v[104:107], v[220:223], v[228:231], v[104:107]
	v_mfma_f32_16x16x32_bf16 v[100:103], v[232:235], v[228:231], v[100:103]
	v_mfma_f32_16x16x32_bf16 v[96:99], v[236:239], v[228:231], v[96:99]
	ds_read_b128 v[224:227], v215 offset:4096
	ds_read_b128 v[228:231], v215 offset:5120
	s_waitcnt lgkmcnt(2)
	v_mfma_f32_16x16x32_bf16 v[92:95], v[216:219], v[180:183], v[92:95]
	v_lshl_add_u64 v[206:207], v[186:187], 0, s[4:5]
	v_mfma_f32_16x16x32_bf16 v[88:91], v[220:223], v[180:183], v[88:91]
	s_mov_b32 m0, s9
	v_mfma_f32_16x16x32_bf16 v[84:87], v[232:235], v[180:183], v[84:87]
	s_add_i32 s9, s9, 0x2000
	v_mfma_f32_16x16x32_bf16 v[80:83], v[236:239], v[180:183], v[80:83]
	global_load_lds_dwordx4 v[206:207], off
	v_mfma_f32_16x16x32_bf16 v[76:79], v[216:219], v[210:213], v[76:79]
	v_mfma_f32_16x16x32_bf16 v[72:75], v[220:223], v[210:213], v[72:75]
	v_mfma_f32_16x16x32_bf16 v[68:71], v[232:235], v[210:213], v[68:71]
	v_mfma_f32_16x16x32_bf16 v[64:67], v[236:239], v[210:213], v[64:67]
	ds_read_b128 v[180:183], v215 offset:6144
	ds_read_b128 v[210:213], v215 offset:7168
	s_waitcnt lgkmcnt(2)
	v_mfma_f32_16x16x32_bf16 v[60:63], v[216:219], v[224:227], v[60:63]
	v_lshl_add_u64 v[206:207], v[172:173], 0, s[4:5]
	v_mfma_f32_16x16x32_bf16 v[56:59], v[220:223], v[224:227], v[56:59]
	s_mov_b32 m0, s9
	v_mfma_f32_16x16x32_bf16 v[52:55], v[232:235], v[224:227], v[52:55]
	s_add_i32 s9, s9, 0x2000
	v_mfma_f32_16x16x32_bf16 v[48:51], v[236:239], v[224:227], v[48:51]
	global_load_lds_dwordx4 v[206:207], off
	v_mfma_f32_16x16x32_bf16 v[44:47], v[216:219], v[228:231], v[44:47]
	v_mfma_f32_16x16x32_bf16 v[40:43], v[220:223], v[228:231], v[40:43]
	v_mfma_f32_16x16x32_bf16 v[36:39], v[232:235], v[228:231], v[36:39]
	v_mfma_f32_16x16x32_bf16 v[32:35], v[236:239], v[228:231], v[32:35]
	s_add_i32 s8, s8, 0x8000
	s_and_b32 s8, s8, 0x18000
	s_waitcnt vmcnt(7) lgkmcnt(0)
	s_barrier
	v_add3_u32 v252, v205, v147, s8
	v_add3_u32 v215, v205, v151, s8
	s_nop 0
	ds_read_b128 v[240:243], v252 offset:16384
	ds_read_b128 v[244:247], v252 offset:17408
	ds_read_b128 v[248:251], v252 offset:18432
	ds_read_b128 v[176:179], v252 offset:19456
	ds_read_b128 v[224:227], v215
	ds_read_b128 v[228:231], v215 offset:1024
	v_mfma_f32_16x16x32_bf16 v[28:31], v[216:219], v[180:183], v[28:31]
	v_lshl_add_u64 v[206:207], v[174:175], 0, s[4:5]
	v_mfma_f32_16x16x32_bf16 v[24:27], v[220:223], v[180:183], v[24:27]
	s_mov_b32 m0, s9
	v_mfma_f32_16x16x32_bf16 v[20:23], v[232:235], v[180:183], v[20:23]
	s_add_i32 s9, s9, 0x2000
	v_mfma_f32_16x16x32_bf16 v[16:19], v[236:239], v[180:183], v[16:19]
	global_load_lds_dwordx4 v[206:207], off
	v_mfma_f32_16x16x32_bf16 v[12:15], v[216:219], v[210:213], v[12:15]
	s_add_u32 s4, s4, 64
	v_mfma_f32_16x16x32_bf16 v[8:11], v[220:223], v[210:213], v[8:11]
	s_addc_u32 s5, s5, 0
	v_mfma_f32_16x16x32_bf16 v[4:7], v[232:235], v[210:213], v[4:7]
	v_mfma_f32_16x16x32_bf16 v[0:3], v[236:239], v[210:213], v[0:3]
	ds_read_b128 v[180:183], v215 offset:2048
	ds_read_b128 v[210:213], v215 offset:3072
	s_waitcnt lgkmcnt(2)
	v_mfma_f32_16x16x32_bf16 v[124:127], v[240:243], v[224:227], v[124:127]
	v_mfma_f32_16x16x32_bf16 v[120:123], v[244:247], v[224:227], v[120:123]
	v_mfma_f32_16x16x32_bf16 v[116:119], v[248:251], v[224:227], v[116:119]
	v_mfma_f32_16x16x32_bf16 v[112:115], v[176:179], v[224:227], v[112:115]
	v_mfma_f32_16x16x32_bf16 v[108:111], v[240:243], v[228:231], v[108:111]
	v_mfma_f32_16x16x32_bf16 v[104:107], v[244:247], v[228:231], v[104:107]
	v_mfma_f32_16x16x32_bf16 v[100:103], v[248:251], v[228:231], v[100:103]
	v_mfma_f32_16x16x32_bf16 v[96:99], v[176:179], v[228:231], v[96:99]
	ds_read_b128 v[224:227], v215 offset:4096
	ds_read_b128 v[228:231], v215 offset:5120
	s_waitcnt lgkmcnt(2)
	v_mfma_f32_16x16x32_bf16 v[92:95], v[240:243], v[180:183], v[92:95]
	v_mfma_f32_16x16x32_bf16 v[88:91], v[244:247], v[180:183], v[88:91]
	v_mfma_f32_16x16x32_bf16 v[84:87], v[248:251], v[180:183], v[84:87]
	v_mfma_f32_16x16x32_bf16 v[80:83], v[176:179], v[180:183], v[80:83]
	v_mfma_f32_16x16x32_bf16 v[76:79], v[240:243], v[210:213], v[76:79]
	v_mfma_f32_16x16x32_bf16 v[72:75], v[244:247], v[210:213], v[72:75]
	v_mfma_f32_16x16x32_bf16 v[68:71], v[248:251], v[210:213], v[68:71]
	v_mfma_f32_16x16x32_bf16 v[64:67], v[176:179], v[210:213], v[64:67]
	ds_read_b128 v[180:183], v215 offset:6144
	ds_read_b128 v[210:213], v215 offset:7168
	s_waitcnt lgkmcnt(2)
	v_mfma_f32_16x16x32_bf16 v[60:63], v[240:243], v[224:227], v[60:63]
	v_mfma_f32_16x16x32_bf16 v[56:59], v[244:247], v[224:227], v[56:59]
	v_mfma_f32_16x16x32_bf16 v[52:55], v[248:251], v[224:227], v[52:55]
	v_mfma_f32_16x16x32_bf16 v[48:51], v[176:179], v[224:227], v[48:51]
	v_mfma_f32_16x16x32_bf16 v[44:47], v[240:243], v[228:231], v[44:47]
	v_mfma_f32_16x16x32_bf16 v[40:43], v[244:247], v[228:231], v[40:43]
	v_mfma_f32_16x16x32_bf16 v[36:39], v[248:251], v[228:231], v[36:39]
	v_mfma_f32_16x16x32_bf16 v[32:35], v[176:179], v[228:231], v[32:35]
	s_add_i32 s8, s8, 0x8000
	s_and_b32 s8, s8, 0x18000
	s_waitcnt vmcnt(4) lgkmcnt(0)
	s_barrier
; template <class Epi>
; DI void gemm_tile256(const u16* __restrict__ Ag, long lda, const u16* __restrict__ Bg, long ldb, int nk, char* shm, Epi&& epi) {
;     ...
;   for (int i = 0; i < nk; ++i) {
;     if (i + 2 < nk) asm volatile("s_waitcnt vmcnt(8)" ::: "memory");
;     else if (i + 1 < nk) asm volatile("s_waitcnt vmcnt(4)" ::: "memory");
;     else asm volatile("s_waitcnt vmcnt(0)" ::: "memory");
;     __builtin_amdgcn_s_barrier();
;     const char* SA = shm + (i & 3) * 32768; const char* SB = SA + 16384;
;     bf16x8 At[8], Bt[4];
; #pragma unroll
;     for (int n = 0; n < 4; ++n) { const int rb = wc * 64 + n * 16 + fr; Bt[n] = *reinterpret_cast<const bf16x8*>(SB + rb * 64 + ((fq ^ ((rb >> 2) & 3)) * 16)); }
; #pragma unroll
;     for (int m = 0; m < 8; ++m) { const int ra = wr * 128 + m * 16 + fr; At[m] = *reinterpret_cast<const bf16x8*>(SA + ra * 64 + ((fq ^ ((ra >> 2) & 3)) * 16)); }
;     if (i + 3 < nk) stage(i + 3);
; #pragma unroll
;     for (int m = 0; m < 8; ++m)
; #pragma unroll
;       for (int n = 0; n < 4; ++n) acc[m][n] = __builtin_amdgcn_mfma_f32_16x16x32_bf16(Bt[n], At[m], acc[m][n], 0, 0, 0);
;   }
;   __syncthreads();
	v_add3_u32 v252, v205, v147, s8
	v_add3_u32 v215, v205, v151, s8
	s_nop 0
	ds_read_b128 v[216:219], v252 offset:16384
	ds_read_b128 v[220:223], v252 offset:17408
	ds_read_b128 v[232:235], v252 offset:18432
	ds_read_b128 v[236:239], v252 offset:19456
	ds_read_b128 v[224:227], v215
	ds_read_b128 v[228:231], v215 offset:1024
	v_mfma_f32_16x16x32_bf16 v[28:31], v[240:243], v[180:183], v[28:31]
	v_mfma_f32_16x16x32_bf16 v[24:27], v[244:247], v[180:183], v[24:27]
	v_mfma_f32_16x16x32_bf16 v[20:23], v[248:251], v[180:183], v[20:23]
	v_mfma_f32_16x16x32_bf16 v[16:19], v[176:179], v[180:183], v[16:19]
	v_mfma_f32_16x16x32_bf16 v[12:15], v[240:243], v[210:213], v[12:15]
	v_mfma_f32_16x16x32_bf16 v[8:11], v[244:247], v[210:213], v[8:11]
	v_mfma_f32_16x16x32_bf16 v[4:7], v[248:251], v[210:213], v[4:7]
	v_mfma_f32_16x16x32_bf16 v[0:3], v[176:179], v[210:213], v[0:3]
	ds_read_b128 v[180:183], v215 offset:2048
	ds_read_b128 v[210:213], v215 offset:3072
	s_waitcnt lgkmcnt(2)
	v_mfma_f32_16x16x32_bf16 v[124:127], v[216:219], v[224:227], v[124:127]
	v_mfma_f32_16x16x32_bf16 v[120:123], v[220:223], v[224:227], v[120:123]
	v_mfma_f32_16x16x32_bf16 v[116:119], v[232:235], v[224:227], v[116:119]
	v_mfma_f32_16x16x32_bf16 v[112:115], v[236:239], v[224:227], v[112:115]
	v_mfma_f32_16x16x32_bf16 v[108:111], v[216:219], v[228:231], v[108:111]
	v_mfma_f32_16x16x32_bf16 v[104:107], v[220:223], v[228:231], v[104:107]
	v_mfma_f32_16x16x32_bf16 v[100:103], v[232:235], v[228:231], v[100:103]
	v_mfma_f32_16x16x32_bf16 v[96:99], v[236:239], v[228:231], v[96:99]
	ds_read_b128 v[224:227], v215 offset:4096
	ds_read_b128 v[228:231], v215 offset:5120
	s_waitcnt lgkmcnt(2)
	v_mfma_f32_16x16x32_bf16 v[92:95], v[216:219], v[180:183], v[92:95]
	v_mfma_f32_16x16x32_bf16 v[88:91], v[220:223], v[180:183], v[88:91]
	v_mfma_f32_16x16x32_bf16 v[84:87], v[232:235], v[180:183], v[84:87]
	v_mfma_f32_16x16x32_bf16 v[80:83], v[236:239], v[180:183], v[80:83]
	v_mfma_f32_16x16x32_bf16 v[76:79], v[216:219], v[210:213], v[76:79]
	v_mfma_f32_16x16x32_bf16 v[72:75], v[220:223], v[210:213], v[72:75]
	v_mfma_f32_16x16x32_bf16 v[68:71], v[232:235], v[210:213], v[68:71]
	v_mfma_f32_16x16x32_bf16 v[64:67], v[236:239], v[210:213], v[64:67]
	ds_read_b128 v[180:183], v215 offset:6144
	ds_read_b128 v[210:213], v215 offset:7168
	s_waitcnt lgkmcnt(2)
	v_mfma_f32_16x16x32_bf16 v[60:63], v[216:219], v[224:227], v[60:63]
	v_mfma_f32_16x16x32_bf16 v[56:59], v[220:223], v[224:227], v[56:59]
	v_mfma_f32_16x16x32_bf16 v[52:55], v[232:235], v[224:227], v[52:55]
	v_mfma_f32_16x16x32_bf16 v[48:51], v[236:239], v[224:227], v[48:51]
	v_mfma_f32_16x16x32_bf16 v[44:47], v[216:219], v[228:231], v[44:47]
	v_mfma_f32_16x16x32_bf16 v[40:43], v[220:223], v[228:231], v[40:43]
	v_mfma_f32_16x16x32_bf16 v[36:39], v[232:235], v[228:231], v[36:39]
	v_mfma_f32_16x16x32_bf16 v[32:35], v[236:239], v[228:231], v[32:35]
	s_add_i32 s8, s8, 0x8000
	s_and_b32 s8, s8, 0x18000
	s_waitcnt vmcnt(0) lgkmcnt(0)
	s_barrier
; DI unsigned pack2bf(float a, float b) { const f2_t v = {a, b}; return __builtin_bit_cast(unsigned, __builtin_convertvector(v, bf2_t)); }
; DI u16 f2bf(float x) { return (u16)(pack2bf(x, 0.f) & 0xffffu); }
; template <class Epi>
; DI void gemm_tile256(const u16* __restrict__ Ag, long lda, const u16* __restrict__ Bg, long ldb, int nk, char* shm, Epi&& epi) {
;     ...
;     for (int m = 0; m < 8; ++m)
; #pragma unroll
;       for (int n = 0; n < 4; ++n) acc[m][n] = __builtin_amdgcn_mfma_f32_16x16x32_bf16(Bt[n], At[m], acc[m][n], 0, 0, 0);
;   }
;   __syncthreads();
; #pragma unroll
;   for (int m = 0; m < 8; ++m)
; #pragma unroll
;     for (int n = 0; n < 4; ++n) epi(wr * 128 + m * 16 + fr, wc * 64 + n * 16 + fq * 4, acc[m][n]);
; DI void phase1(const Params& P, char* smem) {
;     ...
;       const int r = brow + row, c = bcol + col0;
;       const uint2 pk = make_uint2(pack2bf(v[0], v[1]), pack2bf(v[2], v[3]));
;       if (bcol < 512) {
;         const int g = c >> 4, hp = c & 15, m = r >> 6, j = r & 63;
;         *reinterpret_cast<uint2*>(UG + ((long)g * 512 + m) * UGLD + j * 16 + hp) = pk;
;       } else if (bcol < 1024) {
;         *reinterpret_cast<uint2*>(Qb + (long)r * 512 + (c - 512)) = pk;
;       } else if (bcol < 1536) {
;         *reinterpret_cast<uint2*>(Kb + (long)r * 512 + (c - 1024)) = pk;
;       } else {
;         const int hd = c - 1536, b = r >> 13, l = r & 8191;
; #pragma unroll
;         for (int j = 0; j < 4; ++j) Vt[((long)(b * 512 + hd + j)) * 8192 + l] = f2bf(v[j]);
	v_add3_u32 v252, v205, v147, s8
	v_add3_u32 v215, v205, v151, s8
	s_nop 0
	ds_read_b128 v[240:243], v252 offset:16384
	ds_read_b128 v[244:247], v252 offset:17408
	ds_read_b128 v[248:251], v252 offset:18432
	ds_read_b128 v[176:179], v252 offset:19456
	ds_read_b128 v[224:227], v215
	ds_read_b128 v[228:231], v215 offset:1024
	v_mfma_f32_16x16x32_bf16 v[28:31], v[216:219], v[180:183], v[28:31]
	v_mfma_f32_16x16x32_bf16 v[24:27], v[220:223], v[180:183], v[24:27]
	v_mfma_f32_16x16x32_bf16 v[20:23], v[232:235], v[180:183], v[20:23]
	v_mfma_f32_16x16x32_bf16 v[16:19], v[236:239], v[180:183], v[16:19]
	v_mfma_f32_16x16x32_bf16 v[12:15], v[216:219], v[210:213], v[12:15]
	v_mfma_f32_16x16x32_bf16 v[8:11], v[220:223], v[210:213], v[8:11]
	v_mfma_f32_16x16x32_bf16 v[4:7], v[232:235], v[210:213], v[4:7]
	v_mfma_f32_16x16x32_bf16 v[0:3], v[236:239], v[210:213], v[0:3]
	ds_read_b128 v[180:183], v215 offset:2048
	ds_read_b128 v[210:213], v215 offset:3072
	s_waitcnt lgkmcnt(2)
	v_mfma_f32_16x16x32_bf16 v[124:127], v[240:243], v[224:227], v[124:127]
	v_mfma_f32_16x16x32_bf16 v[120:123], v[244:247], v[224:227], v[120:123]
	v_mfma_f32_16x16x32_bf16 v[116:119], v[248:251], v[224:227], v[116:119]
	v_mfma_f32_16x16x32_bf16 v[112:115], v[176:179], v[224:227], v[112:115]
	v_mfma_f32_16x16x32_bf16 v[108:111], v[240:243], v[228:231], v[108:111]
	v_mfma_f32_16x16x32_bf16 v[104:107], v[244:247], v[228:231], v[104:107]
	v_mfma_f32_16x16x32_bf16 v[100:103], v[248:251], v[228:231], v[100:103]
	v_mfma_f32_16x16x32_bf16 v[96:99], v[176:179], v[228:231], v[96:99]
	ds_read_b128 v[224:227], v215 offset:4096
	ds_read_b128 v[228:231], v215 offset:5120
	s_waitcnt lgkmcnt(2)
	v_mfma_f32_16x16x32_bf16 v[92:95], v[240:243], v[180:183], v[92:95]
	v_mfma_f32_16x16x32_bf16 v[88:91], v[244:247], v[180:183], v[88:91]
	v_mfma_f32_16x16x32_bf16 v[84:87], v[248:251], v[180:183], v[84:87]
	v_mfma_f32_16x16x32_bf16 v[80:83], v[176:179], v[180:183], v[80:83]
	v_mfma_f32_16x16x32_bf16 v[76:79], v[240:243], v[210:213], v[76:79]
	v_mfma_f32_16x16x32_bf16 v[72:75], v[244:247], v[210:213], v[72:75]
	v_mfma_f32_16x16x32_bf16 v[68:71], v[248:251], v[210:213], v[68:71]
	v_mfma_f32_16x16x32_bf16 v[64:67], v[176:179], v[210:213], v[64:67]
	ds_read_b128 v[180:183], v215 offset:6144
	ds_read_b128 v[210:213], v215 offset:7168
	s_waitcnt lgkmcnt(2)
	v_mfma_f32_16x16x32_bf16 v[60:63], v[240:243], v[224:227], v[60:63]
	v_mfma_f32_16x16x32_bf16 v[56:59], v[244:247], v[224:227], v[56:59]
	v_mfma_f32_16x16x32_bf16 v[52:55], v[248:251], v[224:227], v[52:55]
	v_mfma_f32_16x16x32_bf16 v[48:51], v[176:179], v[224:227], v[48:51]
	v_mfma_f32_16x16x32_bf16 v[44:47], v[240:243], v[228:231], v[44:47]
	v_mfma_f32_16x16x32_bf16 v[40:43], v[244:247], v[228:231], v[40:43]
	v_mfma_f32_16x16x32_bf16 v[36:39], v[248:251], v[228:231], v[36:39]
	v_mfma_f32_16x16x32_bf16 v[32:35], v[176:179], v[228:231], v[32:35]
	s_waitcnt lgkmcnt(0)
	v_mfma_f32_16x16x32_bf16 v[28:31], v[240:243], v[180:183], v[28:31]
	v_mfma_f32_16x16x32_bf16 v[24:27], v[244:247], v[180:183], v[24:27]
	v_mfma_f32_16x16x32_bf16 v[20:23], v[248:251], v[180:183], v[20:23]
	v_mfma_f32_16x16x32_bf16 v[16:19], v[176:179], v[180:183], v[16:19]
	v_mfma_f32_16x16x32_bf16 v[12:15], v[240:243], v[210:213], v[12:15]
	v_mfma_f32_16x16x32_bf16 v[8:11], v[244:247], v[210:213], v[8:11]
	v_mfma_f32_16x16x32_bf16 v[4:7], v[248:251], v[210:213], v[4:7]
	v_mfma_f32_16x16x32_bf16 v[0:3], v[176:179], v[210:213], v[0:3]
	s_nop 7
	s_nop 3
	v_or_b32_e32 v212, 0x50, v153
	v_or_b32_e32 v213, 0x60, v153
	s_mov_b64 s[4:5], -1
	s_and_b64 vcc, exec, s[10:11]
	s_waitcnt vmcnt(0) lgkmcnt(0)
	s_barrier
	v_add_u32_e32 v184, s30, v153
	v_cvt_pk_bf16_f32 v186, v124, v125
	v_cvt_pk_bf16_f32 v187, v126, v127
	s_cbranch_vccz .LBB0_119
	s_and_b64 vcc, exec, s[18:19]
	s_cbranch_vccz .LBB0_116
	s_and_b64 vcc, exec, s[24:25]
	s_cbranch_vccz .LBB0_113
	v_ashrrev_i32_e32 v215, 4, v184
	v_and_b32_e32 v215, 0xfffffe00, v215
	v_and_b32_e32 v185, 0x1f8f, v184
	v_add_u32_e32 v216, v215, v155
	v_lshlrev_b32_e32 v218, 1, v185
	v_mov_b32_e32 v219, v135
	v_ashrrev_i32_e32 v217, 31, v216
	v_lshl_add_u64 v[218:219], s[62:63], 0, v[218:219]
	v_lshlrev_b64 v[220:221], 14, v[216:217]
	v_cvt_pk_bf16_f32 v124, v124, s0
	v_lshl_add_u64 v[220:221], v[218:219], 0, v[220:221]
	global_store_short v[220:221], v124, off
	v_or_b32_e32 v124, 1, v216
	v_cvt_pk_bf16_f32 v185, v125, s0
	v_ashrrev_i32_e32 v125, 31, v124
	v_lshlrev_b64 v[124:125], 14, v[124:125]
	v_lshl_add_u64 v[124:125], v[218:219], 0, v[124:125]
	global_store_short v[124:125], v185, off
	v_or_b32_e32 v124, 2, v216
	v_ashrrev_i32_e32 v125, 31, v124
	v_lshlrev_b64 v[124:125], 14, v[124:125]
	v_cvt_pk_bf16_f32 v126, v126, s0
	v_lshl_add_u64 v[124:125], v[218:219], 0, v[124:125]
	global_store_short v[124:125], v126, off
	v_or_b32_e32 v124, 3, v216
	v_ashrrev_i32_e32 v125, 31, v124
	v_lshlrev_b64 v[124:125], 14, v[124:125]
	v_cvt_pk_bf16_f32 v126, v127, s0
	v_lshl_add_u64 v[124:125], v[218:219], 0, v[124:125]
	global_store_short v[124:125], v126, off
	s_mov_b64 s[4:5], 0

; template <class Epi>
; DI void gemm_tile256(const u16* __restrict__ Ag, long lda, const u16* __restrict__ Bg, long ldb, int nk, char* shm, Epi&& epi) {
;     ...
;   const int q0 = tid, q1 = 512 + tid;
;   const int r0 = q0 >> 2, r1 = q1 >> 2, c0 = (q0 & 3) ^ ((r0 >> 2) & 3), c1 = (q1 & 3) ^ ((r1 >> 2) & 3);
;   const u16* a0 = Ag + (long)r0 * lda + c0 * 8; const u16* a1 = Ag + (long)r1 * lda + c1 * 8;
;   const u16* b0 = Bg + (long)r0 * ldb + c0 * 8; const u16* b1 = Bg + (long)r1 * ldb + c1 * 8;
;   auto stage = [&](int j) {
;     char* SA = shm + (j & 3) * 32768; char* SB = SA + 16384;
;     __builtin_amdgcn_global_load_lds((const unsigned*)(a0 + j * 32), (__attribute__((address_space(3))) unsigned*)(SA + q0 * 16), 16, 0, 0);
;     __builtin_amdgcn_global_load_lds((const unsigned*)(a1 + j * 32), (__attribute__((address_space(3))) unsigned*)(SA + q1 * 16), 16, 0, 0);
;     __builtin_amdgcn_global_load_lds((const unsigned*)(b0 + j * 32), (__attribute__((address_space(3))) unsigned*)(SB + q0 * 16), 16, 0, 0);
;     __builtin_amdgcn_global_load_lds((const unsigned*)(b1 + j * 32), (__attribute__((address_space(3))) unsigned*)(SB + q1 * 16), 16, 0, 0);
;   };
;   __syncthreads();
;   stage(0);
;   if (nk > 1) stage(1);
;   if (nk > 2) stage(2);
;   for (int i = 0; i < nk; ++i) {
;     if (i + 2 < nk) asm volatile("s_waitcnt vmcnt(8)" ::: "memory");
;     else if (i + 1 < nk) asm volatile("s_waitcnt vmcnt(4)" ::: "memory");
;     else asm volatile("s_waitcnt vmcnt(0)" ::: "memory");
;     __builtin_amdgcn_s_barrier();
;     const char* SA = shm + (i & 3) * 32768; const char* SB = SA + 16384;
; DI void phase6(const Params& P, char* smem) {
;     ...
;   for (int q = RBLK >> 3; q < 64; q += RGRID >> 3) {
;     const int brow = (q * 2 + ((RBLK & 7) >> 2)) * 256, bcol = (RBLK & 3) * 256;
;     gemm_tile256(cat + (long)brow * 1024, 1024, WoT + (long)bcol * 1024, 1024, 32, smem, [&](int row, int col0, f32x4 v) {
.LBB0_946:
	s_ashr_i32 s5, s4, 31
	s_lshl_b64 s[10:11], s[4:5], 11
	s_lshl_b32 s5, s15, 9
	v_lshl_add_u64 v[164:165], v[156:157], 0, s[10:11]
	v_lshl_add_u64 v[166:167], v[158:159], 0, s[10:11]
	s_or_b32 s10, s5, s2
	s_ashr_i32 s11, s10, 31
	s_lshl_b64 s[12:13], s[10:11], 11
	s_add_u32 s12, s62, s12
	s_addc_u32 s13, s63, s13
	v_add_u32_e32 v6, 0, v209
	v_lshl_add_u64 v[0:1], s[12:13], 0, v[130:131]
	v_readfirstlane_b32 s5, v6
	v_add_u32_e32 v7, 0, v149
	v_lshl_add_u64 v[0:1], v[0:1], 0, v[132:133]
	v_lshl_add_u64 v[2:3], s[12:13], 0, v[134:135]
	s_mov_b32 m0, s5
	v_readfirstlane_b32 s5, v7
	v_add_u32_e32 v4, 0x4000, v6
	v_lshl_add_u64 v[2:3], v[2:3], 0, v[132:133]
	s_barrier
	global_load_lds_dwordx4 v[0:1], off
	s_mov_b32 m0, s5
	v_readfirstlane_b32 s5, v4
	v_add_u32_e32 v4, 0x4000, v7
	global_load_lds_dwordx4 v[2:3], off
	s_mov_b32 m0, s5
	v_readfirstlane_b32 s5, v4
	v_add_u32_e32 v8, 0x8000, v6
	global_load_lds_dwordx4 v[136:137], off
	s_mov_b32 m0, s5
	v_readfirstlane_b32 s5, v8
	v_add_u32_e32 v8, 0x8000, v7
	global_load_lds_dwordx4 v[138:139], off
	v_lshl_add_u64 v[4:5], v[0:1], 0, 64
	s_mov_b32 m0, s5
	v_readfirstlane_b32 s5, v8
	global_load_lds_dwordx4 v[4:5], off
	v_lshl_add_u64 v[4:5], v[2:3], 0, 64
	s_mov_b32 m0, s5
	v_lshl_add_u64 v[0:1], v[0:1], 0, s[0:1]
	global_load_lds_dwordx4 v[4:5], off
	v_add_u32_e32 v4, 0xc000, v6
	s_mov_b64 s[12:13], 0
	v_readfirstlane_b32 s5, v4
	v_add_u32_e32 v4, 0xc000, v7
	s_mov_b32 m0, s5
	v_readfirstlane_b32 s5, v4
	v_add_u32_e32 v4, s7, v209
	global_load_lds_dwordx4 v[140:141], off
	s_mov_b32 m0, s5
	v_readfirstlane_b32 s5, v4
	global_load_lds_dwordx4 v[142:143], off
	s_mov_b32 m0, s5
	v_mov_b32_e32 v4, 0
	global_load_lds_dwordx4 v[0:1], off
	v_lshl_add_u64 v[0:1], v[2:3], 0, s[0:1]
	v_add_u32_e32 v2, s7, v149
	v_mov_b32_e32 v3, v133
	v_readfirstlane_b32 s5, v2
	s_mov_b32 m0, s5
	v_mov_b32_e32 v2, v133
	global_load_lds_dwordx4 v[0:1], off
	v_add_u32_e32 v0, s8, v209
	v_mov_b32_e32 v1, v133
	v_readfirstlane_b32 s5, v0
	v_add_u32_e32 v0, s8, v149
	s_mov_b32 m0, s5
	v_readfirstlane_b32 s5, v0
	global_load_lds_dwordx4 v[144:145], off
	s_mov_b32 m0, s5
	s_mov_b32 s5, 0x18000
	global_load_lds_dwordx4 v[146:147], off
	v_mov_b32_e32 v0, 0
	v_mov_b32_e32 v5, v133
	v_mov_b32_e32 v6, v133
	v_mov_b32_e32 v7, v133
	v_mov_b32_e32 v8, 0
	v_mov_b32_e32 v9, v133
	v_mov_b32_e32 v10, v133
	v_mov_b32_e32 v11, v133
	v_mov_b32_e32 v12, 0
	v_mov_b32_e32 v13, v133
	v_mov_b32_e32 v14, v133
	v_mov_b32_e32 v15, v133
	v_mov_b32_e32 v16, 0
	v_mov_b32_e32 v17, v133
	v_mov_b32_e32 v18, v133
	v_mov_b32_e32 v19, v133
	v_mov_b32_e32 v20, 0
	v_mov_b32_e32 v21, v133
	v_mov_b32_e32 v22, v133
	v_mov_b32_e32 v23, v133
	v_mov_b32_e32 v24, 0
	v_mov_b32_e32 v25, v133
	v_mov_b32_e32 v26, v133
	v_mov_b32_e32 v27, v133
	v_mov_b32_e32 v28, 0
	v_mov_b32_e32 v29, v133
	v_mov_b32_e32 v30, v133
	v_mov_b32_e32 v31, v133
	v_mov_b32_e32 v32, 0
	v_mov_b32_e32 v33, v133
	v_mov_b32_e32 v34, v133
	v_mov_b32_e32 v35, v133
	v_mov_b32_e32 v36, 0
	v_mov_b32_e32 v37, v133
	v_mov_b32_e32 v38, v133
	v_mov_b32_e32 v39, v133
	v_mov_b32_e32 v40, 0
	v_mov_b32_e32 v41, v133
	v_mov_b32_e32 v42, v133
	v_mov_b32_e32 v43, v133
	v_mov_b32_e32 v44, 0
	v_mov_b32_e32 v45, v133
	v_mov_b32_e32 v46, v133
	v_mov_b32_e32 v47, v133
	v_mov_b32_e32 v48, 0
	v_mov_b32_e32 v49, v133
	v_mov_b32_e32 v50, v133
	v_mov_b32_e32 v51, v133
	v_mov_b32_e32 v52, 0
	v_mov_b32_e32 v53, v133
	v_mov_b32_e32 v54, v133
	v_mov_b32_e32 v55, v133
	v_mov_b32_e32 v56, 0
	v_mov_b32_e32 v57, v133
	v_mov_b32_e32 v58, v133
	v_mov_b32_e32 v59, v133
	v_mov_b32_e32 v60, 0
	v_mov_b32_e32 v61, v133
	v_mov_b32_e32 v62, v133
	v_mov_b32_e32 v63, v133
	v_mov_b32_e32 v64, 0
	v_mov_b32_e32 v65, v133
	v_mov_b32_e32 v66, v133
	v_mov_b32_e32 v67, v133
	v_mov_b32_e32 v68, 0
	v_mov_b32_e32 v69, v133
	v_mov_b32_e32 v70, v133
	v_mov_b32_e32 v71, v133
	v_mov_b32_e32 v72, 0
	v_mov_b32_e32 v73, v133
	v_mov_b32_e32 v74, v133
	v_mov_b32_e32 v75, v133
	v_mov_b32_e32 v76, 0
	v_mov_b32_e32 v77, v133
	v_mov_b32_e32 v78, v133
	v_mov_b32_e32 v79, v133
	v_mov_b32_e32 v80, 0
	v_mov_b32_e32 v81, v133
	v_mov_b32_e32 v82, v133
	v_mov_b32_e32 v83, v133
	v_mov_b32_e32 v84, 0
	v_mov_b32_e32 v85, v133
	v_mov_b32_e32 v86, v133
	v_mov_b32_e32 v87, v133
	v_mov_b32_e32 v88, 0
	v_mov_b32_e32 v89, v133
	v_mov_b32_e32 v90, v133
	v_mov_b32_e32 v91, v133
	v_mov_b32_e32 v92, 0
	v_mov_b32_e32 v93, v133
	v_mov_b32_e32 v94, v133
	v_mov_b32_e32 v95, v133
	v_mov_b32_e32 v96, 0
	v_mov_b32_e32 v97, v133
	v_mov_b32_e32 v98, v133
	v_mov_b32_e32 v99, v133
	v_mov_b32_e32 v100, 0
	v_mov_b32_e32 v101, v133
	v_mov_b32_e32 v102, v133
	v_mov_b32_e32 v103, v133
	v_mov_b32_e32 v104, 0
	v_mov_b32_e32 v105, v133
	v_mov_b32_e32 v106, v133
	v_mov_b32_e32 v107, v133
	v_mov_b32_e32 v108, 0
	v_mov_b32_e32 v109, v133
	v_mov_b32_e32 v110, v133
	v_mov_b32_e32 v111, v133
	v_mov_b32_e32 v112, 0
	v_mov_b32_e32 v113, v133
	v_mov_b32_e32 v114, v133
	v_mov_b32_e32 v115, v133
	v_mov_b32_e32 v116, 0
	v_mov_b32_e32 v117, v133
	v_mov_b32_e32 v118, v133
	v_mov_b32_e32 v119, v133
	v_mov_b32_e32 v120, 0
	v_mov_b32_e32 v121, v133
	v_mov_b32_e32 v122, v133
	v_mov_b32_e32 v123, v133
	v_mov_b32_e32 v124, 0
	v_mov_b32_e32 v125, v133
	v_mov_b32_e32 v126, v133
	v_mov_b32_e32 v127, v133
	v_readfirstlane_b32 s16, v209
	s_mov_b32 s5, 0
	s_mov_b64 s[12:13], 0
	s_waitcnt vmcnt(8)
	s_barrier
	v_add3_u32 v231, v183, v151, s5
	v_add3_u32 v230, v183, v153, s5
	s_nop 0
	ds_read_b128 v[196:199], v231 offset:16384
	ds_read_b128 v[200:203], v231 offset:17408
	ds_read_b128 v[214:217], v231 offset:18432
	ds_read_b128 v[218:221], v231 offset:19456
	ds_read_b128 v[204:207], v230
	ds_read_b128 v[210:213], v230 offset:1024
; template <class Epi>
; DI void gemm_tile256(const u16* __restrict__ Ag, long lda, const u16* __restrict__ Bg, long ldb, int nk, char* shm, Epi&& epi) {
;     ...
;   for (int i = 0; i < nk; ++i) {
;     if (i + 2 < nk) asm volatile("s_waitcnt vmcnt(8)" ::: "memory");
;     else if (i + 1 < nk) asm volatile("s_waitcnt vmcnt(4)" ::: "memory");
;     else asm volatile("s_waitcnt vmcnt(0)" ::: "memory");
;     __builtin_amdgcn_s_barrier();
;     const char* SA = shm + (i & 3) * 32768; const char* SB = SA + 16384;
;     bf16x8 At[8], Bt[4];
; #pragma unroll
;     for (int n = 0; n < 4; ++n) { const int rb = wc * 64 + n * 16 + fr; Bt[n] = *reinterpret_cast<const bf16x8*>(SB + rb * 64 + ((fq ^ ((rb >> 2) & 3)) * 16)); }
; #pragma unroll
;     for (int m = 0; m < 8; ++m) { const int ra = wr * 128 + m * 16 + fr; At[m] = *reinterpret_cast<const bf16x8*>(SA + ra * 64 + ((fq ^ ((ra >> 2) & 3)) * 16)); }
;     if (i + 3 < nk) stage(i + 3);
; #pragma unroll
;     for (int m = 0; m < 8; ++m)
; #pragma unroll
;       for (int n = 0; n < 4; ++n) acc[m][n] = __builtin_amdgcn_mfma_f32_16x16x32_bf16(Bt[n], At[m], acc[m][n], 0, 0, 0);
.Lgemm_p6_kloop:
	s_add_i32 s11, s5, 0x18000
	s_and_b32 s11, s11, 0x18000
	s_add_i32 s17, s11, s16
	ds_read_b128 v[248:251], v230 offset:2048
	ds_read_b128 v[222:225], v230 offset:3072
	s_waitcnt lgkmcnt(2)
	v_mfma_f32_16x16x32_bf16 v[124:127], v[196:199], v[204:207], v[124:127]
	v_lshl_add_u64 v[226:227], v[164:165], 0, s[12:13]
	v_mfma_f32_16x16x32_bf16 v[120:123], v[200:203], v[204:207], v[120:123]
	s_mov_b32 m0, s17
	v_mfma_f32_16x16x32_bf16 v[116:119], v[214:217], v[204:207], v[116:119]
	s_add_i32 s17, s17, 0x2000
	v_mfma_f32_16x16x32_bf16 v[112:115], v[218:221], v[204:207], v[112:115]
	global_load_lds_dwordx4 v[226:227], off
	v_mfma_f32_16x16x32_bf16 v[108:111], v[196:199], v[210:213], v[108:111]
	v_mfma_f32_16x16x32_bf16 v[104:107], v[200:203], v[210:213], v[104:107]
	v_mfma_f32_16x16x32_bf16 v[100:103], v[214:217], v[210:213], v[100:103]
	v_mfma_f32_16x16x32_bf16 v[96:99], v[218:221], v[210:213], v[96:99]
	ds_read_b128 v[204:207], v230 offset:4096
	ds_read_b128 v[210:213], v230 offset:5120
	s_waitcnt lgkmcnt(2)
	v_mfma_f32_16x16x32_bf16 v[92:95], v[196:199], v[248:251], v[92:95]
	v_lshl_add_u64 v[226:227], v[166:167], 0, s[12:13]
	v_mfma_f32_16x16x32_bf16 v[88:91], v[200:203], v[248:251], v[88:91]
	s_mov_b32 m0, s17
	v_mfma_f32_16x16x32_bf16 v[84:87], v[214:217], v[248:251], v[84:87]
	s_add_i32 s17, s17, 0x2000
	v_mfma_f32_16x16x32_bf16 v[80:83], v[218:221], v[248:251], v[80:83]
	global_load_lds_dwordx4 v[226:227], off
	v_mfma_f32_16x16x32_bf16 v[76:79], v[196:199], v[222:225], v[76:79]
	v_mfma_f32_16x16x32_bf16 v[72:75], v[200:203], v[222:225], v[72:75]
	v_mfma_f32_16x16x32_bf16 v[68:71], v[214:217], v[222:225], v[68:71]
	v_mfma_f32_16x16x32_bf16 v[64:67], v[218:221], v[222:225], v[64:67]
	ds_read_b128 v[248:251], v230 offset:6144
	ds_read_b128 v[222:225], v230 offset:7168
	s_waitcnt lgkmcnt(2)
	v_mfma_f32_16x16x32_bf16 v[60:63], v[196:199], v[204:207], v[60:63]
	v_lshl_add_u64 v[226:227], v[160:161], 0, s[12:13]
	v_mfma_f32_16x16x32_bf16 v[56:59], v[200:203], v[204:207], v[56:59]
	s_mov_b32 m0, s17
	v_mfma_f32_16x16x32_bf16 v[52:55], v[214:217], v[204:207], v[52:55]
	s_add_i32 s17, s17, 0x2000
	v_mfma_f32_16x16x32_bf16 v[48:51], v[218:221], v[204:207], v[48:51]
	global_load_lds_dwordx4 v[226:227], off
	v_mfma_f32_16x16x32_bf16 v[44:47], v[196:199], v[210:213], v[44:47]
	v_mfma_f32_16x16x32_bf16 v[40:43], v[200:203], v[210:213], v[40:43]
	v_mfma_f32_16x16x32_bf16 v[36:39], v[214:217], v[210:213], v[36:39]
	v_mfma_f32_16x16x32_bf16 v[32:35], v[218:221], v[210:213], v[32:35]
	s_add_i32 s5, s5, 0x8000
	s_and_b32 s5, s5, 0x18000
	s_waitcnt vmcnt(7) lgkmcnt(0)
	s_barrier
	v_add3_u32 v231, v183, v151, s5
	v_add3_u32 v230, v183, v153, s5
	s_nop 0
	ds_read_b128 v[232:235], v231 offset:16384
	ds_read_b128 v[236:239], v231 offset:17408
	ds_read_b128 v[240:243], v231 offset:18432
	ds_read_b128 v[244:247], v231 offset:19456
	ds_read_b128 v[204:207], v230
	ds_read_b128 v[210:213], v230 offset:1024
	v_mfma_f32_16x16x32_bf16 v[28:31], v[196:199], v[248:251], v[28:31]
	v_lshl_add_u64 v[226:227], v[162:163], 0, s[12:13]
	v_mfma_f32_16x16x32_bf16 v[24:27], v[200:203], v[248:251], v[24:27]
	s_mov_b32 m0, s17
	v_mfma_f32_16x16x32_bf16 v[20:23], v[214:217], v[248:251], v[20:23]
	s_add_i32 s17, s17, 0x2000
	v_mfma_f32_16x16x32_bf16 v[16:19], v[218:221], v[248:251], v[16:19]
	global_load_lds_dwordx4 v[226:227], off
	v_mfma_f32_16x16x32_bf16 v[12:15], v[196:199], v[222:225], v[12:15]
	s_add_u32 s12, s12, 64
	v_mfma_f32_16x16x32_bf16 v[8:11], v[200:203], v[222:225], v[8:11]
	s_addc_u32 s13, s13, 0
	v_mfma_f32_16x16x32_bf16 v[4:7], v[214:217], v[222:225], v[4:7]
	v_mfma_f32_16x16x32_bf16 v[0:3], v[218:221], v[222:225], v[0:3]
	s_add_i32 s11, s5, 0x18000
	s_and_b32 s11, s11, 0x18000
	s_add_i32 s17, s11, s16
	ds_read_b128 v[248:251], v230 offset:2048
	ds_read_b128 v[222:225], v230 offset:3072
	s_waitcnt lgkmcnt(2)
	v_mfma_f32_16x16x32_bf16 v[124:127], v[232:235], v[204:207], v[124:127]
	v_lshl_add_u64 v[226:227], v[164:165], 0, s[12:13]
	v_mfma_f32_16x16x32_bf16 v[120:123], v[236:239], v[204:207], v[120:123]
	s_mov_b32 m0, s17
	v_mfma_f32_16x16x32_bf16 v[116:119], v[240:243], v[204:207], v[116:119]
	s_add_i32 s17, s17, 0x2000
	v_mfma_f32_16x16x32_bf16 v[112:115], v[244:247], v[204:207], v[112:115]
	global_load_lds_dwordx4 v[226:227], off
	v_mfma_f32_16x16x32_bf16 v[108:111], v[232:235], v[210:213], v[108:111]
	v_mfma_f32_16x16x32_bf16 v[104:107], v[236:239], v[210:213], v[104:107]
	v_mfma_f32_16x16x32_bf16 v[100:103], v[240:243], v[210:213], v[100:103]
	v_mfma_f32_16x16x32_bf16 v[96:99], v[244:247], v[210:213], v[96:99]
	ds_read_b128 v[204:207], v230 offset:4096
	ds_read_b128 v[210:213], v230 offset:5120
	s_waitcnt lgkmcnt(2)
	v_mfma_f32_16x16x32_bf16 v[92:95], v[232:235], v[248:251], v[92:95]
	v_lshl_add_u64 v[226:227], v[166:167], 0, s[12:13]
	v_mfma_f32_16x16x32_bf16 v[88:91], v[236:239], v[248:251], v[88:91]
	s_mov_b32 m0, s17
	v_mfma_f32_16x16x32_bf16 v[84:87], v[240:243], v[248:251], v[84:87]
	s_add_i32 s17, s17, 0x2000
	v_mfma_f32_16x16x32_bf16 v[80:83], v[244:247], v[248:251], v[80:83]
	global_load_lds_dwordx4 v[226:227], off
	v_mfma_f32_16x16x32_bf16 v[76:79], v[232:235], v[222:225], v[76:79]
	v_mfma_f32_16x16x32_bf16 v[72:75], v[236:239], v[222:225], v[72:75]
	v_mfma_f32_16x16x32_bf16 v[68:71], v[240:243], v[222:225], v[68:71]
	v_mfma_f32_16x16x32_bf16 v[64:67], v[244:247], v[222:225], v[64:67]
	ds_read_b128 v[248:251], v230 offset:6144
	ds_read_b128 v[222:225], v230 offset:7168
	s_waitcnt lgkmcnt(2)
	v_mfma_f32_16x16x32_bf16 v[60:63], v[232:235], v[204:207], v[60:63]
	v_lshl_add_u64 v[226:227], v[160:161], 0, s[12:13]
	v_mfma_f32_16x16x32_bf16 v[56:59], v[236:239], v[204:207], v[56:59]
	s_mov_b32 m0, s17
	v_mfma_f32_16x16x32_bf16 v[52:55], v[240:243], v[204:207], v[52:55]
	s_add_i32 s17, s17, 0x2000
	v_mfma_f32_16x16x32_bf16 v[48:51], v[244:247], v[204:207], v[48:51]
	global_load_lds_dwordx4 v[226:227], off
	v_mfma_f32_16x16x32_bf16 v[44:47], v[232:235], v[210:213], v[44:47]
	v_mfma_f32_16x16x32_bf16 v[40:43], v[236:239], v[210:213], v[40:43]
	v_mfma_f32_16x16x32_bf16 v[36:39], v[240:243], v[210:213], v[36:39]
	v_mfma_f32_16x16x32_bf16 v[32:35], v[244:247], v[210:213], v[32:35]
	s_add_i32 s5, s5, 0x8000
	s_and_b32 s5, s5, 0x18000
	s_waitcnt vmcnt(7) lgkmcnt(0)
	s_barrier
; template <class Epi>
; DI void gemm_tile256(const u16* __restrict__ Ag, long lda, const u16* __restrict__ Bg, long ldb, int nk, char* shm, Epi&& epi) {
;     ...
;   for (int i = 0; i < nk; ++i) {
;     if (i + 2 < nk) asm volatile("s_waitcnt vmcnt(8)" ::: "memory");
;     else if (i + 1 < nk) asm volatile("s_waitcnt vmcnt(4)" ::: "memory");
;     else asm volatile("s_waitcnt vmcnt(0)" ::: "memory");
;     __builtin_amdgcn_s_barrier();
;     const char* SA = shm + (i & 3) * 32768; const char* SB = SA + 16384;
;     bf16x8 At[8], Bt[4];
; #pragma unroll
;     for (int n = 0; n < 4; ++n) { const int rb = wc * 64 + n * 16 + fr; Bt[n] = *reinterpret_cast<const bf16x8*>(SB + rb * 64 + ((fq ^ ((rb >> 2) & 3)) * 16)); }
; #pragma unroll
;     for (int m = 0; m < 8; ++m) { const int ra = wr * 128 + m * 16 + fr; At[m] = *reinterpret_cast<const bf16x8*>(SA + ra * 64 + ((fq ^ ((ra >> 2) & 3)) * 16)); }
;     if (i + 3 < nk) stage(i + 3);
; #pragma unroll
;     for (int m = 0; m < 8; ++m)
; #pragma unroll
;       for (int n = 0; n < 4; ++n) acc[m][n] = __builtin_amdgcn_mfma_f32_16x16x32_bf16(Bt[n], At[m], acc[m][n], 0, 0, 0);
;   }
	v_add3_u32 v231, v183, v151, s5
	v_add3_u32 v230, v183, v153, s5
	s_nop 0
	ds_read_b128 v[196:199], v231 offset:16384
	ds_read_b128 v[200:203], v231 offset:17408
	ds_read_b128 v[214:217], v231 offset:18432
	ds_read_b128 v[218:221], v231 offset:19456
	ds_read_b128 v[204:207], v230
	ds_read_b128 v[210:213], v230 offset:1024
	v_mfma_f32_16x16x32_bf16 v[28:31], v[232:235], v[248:251], v[28:31]
	v_lshl_add_u64 v[226:227], v[162:163], 0, s[12:13]
	v_mfma_f32_16x16x32_bf16 v[24:27], v[236:239], v[248:251], v[24:27]
	s_mov_b32 m0, s17
	v_mfma_f32_16x16x32_bf16 v[20:23], v[240:243], v[248:251], v[20:23]
	s_add_i32 s17, s17, 0x2000
	v_mfma_f32_16x16x32_bf16 v[16:19], v[244:247], v[248:251], v[16:19]
	global_load_lds_dwordx4 v[226:227], off
	v_mfma_f32_16x16x32_bf16 v[12:15], v[232:235], v[222:225], v[12:15]
	s_add_u32 s12, s12, 64
	v_mfma_f32_16x16x32_bf16 v[8:11], v[236:239], v[222:225], v[8:11]
	s_addc_u32 s13, s13, 0
	v_mfma_f32_16x16x32_bf16 v[4:7], v[240:243], v[222:225], v[4:7]
	v_mfma_f32_16x16x32_bf16 v[0:3], v[244:247], v[222:225], v[0:3]
	s_cmpk_lg_i32 s12, 0x700
	s_cbranch_scc1 .Lgemm_p6_kloop
	s_add_i32 s11, s5, 0x18000
	s_and_b32 s11, s11, 0x18000
	s_add_i32 s17, s11, s16
	ds_read_b128 v[248:251], v230 offset:2048
	ds_read_b128 v[222:225], v230 offset:3072
	s_waitcnt lgkmcnt(2)
	v_mfma_f32_16x16x32_bf16 v[124:127], v[196:199], v[204:207], v[124:127]
	v_lshl_add_u64 v[226:227], v[164:165], 0, s[12:13]
	v_mfma_f32_16x16x32_bf16 v[120:123], v[200:203], v[204:207], v[120:123]
	s_mov_b32 m0, s17
	v_mfma_f32_16x16x32_bf16 v[116:119], v[214:217], v[204:207], v[116:119]
	s_add_i32 s17, s17, 0x2000
	v_mfma_f32_16x16x32_bf16 v[112:115], v[218:221], v[204:207], v[112:115]
	global_load_lds_dwordx4 v[226:227], off
	v_mfma_f32_16x16x32_bf16 v[108:111], v[196:199], v[210:213], v[108:111]
	v_mfma_f32_16x16x32_bf16 v[104:107], v[200:203], v[210:213], v[104:107]
	v_mfma_f32_16x16x32_bf16 v[100:103], v[214:217], v[210:213], v[100:103]
	v_mfma_f32_16x16x32_bf16 v[96:99], v[218:221], v[210:213], v[96:99]
	ds_read_b128 v[204:207], v230 offset:4096
	ds_read_b128 v[210:213], v230 offset:5120
	s_waitcnt lgkmcnt(2)
	v_mfma_f32_16x16x32_bf16 v[92:95], v[196:199], v[248:251], v[92:95]
	v_lshl_add_u64 v[226:227], v[166:167], 0, s[12:13]
	v_mfma_f32_16x16x32_bf16 v[88:91], v[200:203], v[248:251], v[88:91]
	s_mov_b32 m0, s17
	v_mfma_f32_16x16x32_bf16 v[84:87], v[214:217], v[248:251], v[84:87]
	s_add_i32 s17, s17, 0x2000
	v_mfma_f32_16x16x32_bf16 v[80:83], v[218:221], v[248:251], v[80:83]
	global_load_lds_dwordx4 v[226:227], off
	v_mfma_f32_16x16x32_bf16 v[76:79], v[196:199], v[222:225], v[76:79]
	v_mfma_f32_16x16x32_bf16 v[72:75], v[200:203], v[222:225], v[72:75]
	v_mfma_f32_16x16x32_bf16 v[68:71], v[214:217], v[222:225], v[68:71]
	v_mfma_f32_16x16x32_bf16 v[64:67], v[218:221], v[222:225], v[64:67]
	ds_read_b128 v[248:251], v230 offset:6144
	ds_read_b128 v[222:225], v230 offset:7168
	s_waitcnt lgkmcnt(2)
	v_mfma_f32_16x16x32_bf16 v[60:63], v[196:199], v[204:207], v[60:63]
	v_lshl_add_u64 v[226:227], v[160:161], 0, s[12:13]
	v_mfma_f32_16x16x32_bf16 v[56:59], v[200:203], v[204:207], v[56:59]
	s_mov_b32 m0, s17
	v_mfma_f32_16x16x32_bf16 v[52:55], v[214:217], v[204:207], v[52:55]
	s_add_i32 s17, s17, 0x2000
	v_mfma_f32_16x16x32_bf16 v[48:51], v[218:221], v[204:207], v[48:51]
	global_load_lds_dwordx4 v[226:227], off
	v_mfma_f32_16x16x32_bf16 v[44:47], v[196:199], v[210:213], v[44:47]
	v_mfma_f32_16x16x32_bf16 v[40:43], v[200:203], v[210:213], v[40:43]
	v_mfma_f32_16x16x32_bf16 v[36:39], v[214:217], v[210:213], v[36:39]
	v_mfma_f32_16x16x32_bf16 v[32:35], v[218:221], v[210:213], v[32:35]
	s_add_i32 s5, s5, 0x8000
	s_and_b32 s5, s5, 0x18000
	s_waitcnt vmcnt(7) lgkmcnt(0)
	s_barrier
	v_add3_u32 v231, v183, v151, s5
	v_add3_u32 v230, v183, v153, s5
	s_nop 0
	ds_read_b128 v[232:235], v231 offset:16384
	ds_read_b128 v[236:239], v231 offset:17408
	ds_read_b128 v[240:243], v231 offset:18432
	ds_read_b128 v[244:247], v231 offset:19456
	ds_read_b128 v[204:207], v230
	ds_read_b128 v[210:213], v230 offset:1024
	v_mfma_f32_16x16x32_bf16 v[28:31], v[196:199], v[248:251], v[28:31]
	v_lshl_add_u64 v[226:227], v[162:163], 0, s[12:13]
	v_mfma_f32_16x16x32_bf16 v[24:27], v[200:203], v[248:251], v[24:27]
	s_mov_b32 m0, s17
	v_mfma_f32_16x16x32_bf16 v[20:23], v[214:217], v[248:251], v[20:23]
	s_add_i32 s17, s17, 0x2000
	v_mfma_f32_16x16x32_bf16 v[16:19], v[218:221], v[248:251], v[16:19]
	global_load_lds_dwordx4 v[226:227], off
	v_mfma_f32_16x16x32_bf16 v[12:15], v[196:199], v[222:225], v[12:15]
	s_add_u32 s12, s12, 64
	v_mfma_f32_16x16x32_bf16 v[8:11], v[200:203], v[222:225], v[8:11]
	s_addc_u32 s13, s13, 0
	v_mfma_f32_16x16x32_bf16 v[4:7], v[214:217], v[222:225], v[4:7]
	v_mfma_f32_16x16x32_bf16 v[0:3], v[218:221], v[222:225], v[0:3]
	ds_read_b128 v[248:251], v230 offset:2048
	ds_read_b128 v[222:225], v230 offset:3072
	s_waitcnt lgkmcnt(2)
	v_mfma_f32_16x16x32_bf16 v[124:127], v[232:235], v[204:207], v[124:127]
	v_mfma_f32_16x16x32_bf16 v[120:123], v[236:239], v[204:207], v[120:123]
	v_mfma_f32_16x16x32_bf16 v[116:119], v[240:243], v[204:207], v[116:119]
	v_mfma_f32_16x16x32_bf16 v[112:115], v[244:247], v[204:207], v[112:115]
	v_mfma_f32_16x16x32_bf16 v[108:111], v[232:235], v[210:213], v[108:111]
	v_mfma_f32_16x16x32_bf16 v[104:107], v[236:239], v[210:213], v[104:107]
	v_mfma_f32_16x16x32_bf16 v[100:103], v[240:243], v[210:213], v[100:103]
	v_mfma_f32_16x16x32_bf16 v[96:99], v[244:247], v[210:213], v[96:99]
	ds_read_b128 v[204:207], v230 offset:4096
	ds_read_b128 v[210:213], v230 offset:5120
	s_waitcnt lgkmcnt(2)
	v_mfma_f32_16x16x32_bf16 v[92:95], v[232:235], v[248:251], v[92:95]
	v_mfma_f32_16x16x32_bf16 v[88:91], v[236:239], v[248:251], v[88:91]
	v_mfma_f32_16x16x32_bf16 v[84:87], v[240:243], v[248:251], v[84:87]
	v_mfma_f32_16x16x32_bf16 v[80:83], v[244:247], v[248:251], v[80:83]
	v_mfma_f32_16x16x32_bf16 v[76:79], v[232:235], v[222:225], v[76:79]
	v_mfma_f32_16x16x32_bf16 v[72:75], v[236:239], v[222:225], v[72:75]
	v_mfma_f32_16x16x32_bf16 v[68:71], v[240:243], v[222:225], v[68:71]
	v_mfma_f32_16x16x32_bf16 v[64:67], v[244:247], v[222:225], v[64:67]
	ds_read_b128 v[248:251], v230 offset:6144
	ds_read_b128 v[222:225], v230 offset:7168
	s_waitcnt lgkmcnt(2)
	v_mfma_f32_16x16x32_bf16 v[60:63], v[232:235], v[204:207], v[60:63]
	v_mfma_f32_16x16x32_bf16 v[56:59], v[236:239], v[204:207], v[56:59]
	v_mfma_f32_16x16x32_bf16 v[52:55], v[240:243], v[204:207], v[52:55]
	v_mfma_f32_16x16x32_bf16 v[48:51], v[244:247], v[204:207], v[48:51]
	v_mfma_f32_16x16x32_bf16 v[44:47], v[232:235], v[210:213], v[44:47]
	v_mfma_f32_16x16x32_bf16 v[40:43], v[236:239], v[210:213], v[40:43]
	v_mfma_f32_16x16x32_bf16 v[36:39], v[240:243], v[210:213], v[36:39]
	v_mfma_f32_16x16x32_bf16 v[32:35], v[244:247], v[210:213], v[32:35]
	s_add_i32 s5, s5, 0x8000
	s_and_b32 s5, s5, 0x18000
	s_waitcnt vmcnt(4) lgkmcnt(0)
	s_barrier
; template <class Epi>
; DI void gemm_tile256(const u16* __restrict__ Ag, long lda, const u16* __restrict__ Bg, long ldb, int nk, char* shm, Epi&& epi) {
;     ...
;   for (int i = 0; i < nk; ++i) {
;     if (i + 2 < nk) asm volatile("s_waitcnt vmcnt(8)" ::: "memory");
;     else if (i + 1 < nk) asm volatile("s_waitcnt vmcnt(4)" ::: "memory");
;     else asm volatile("s_waitcnt vmcnt(0)" ::: "memory");
;     __builtin_amdgcn_s_barrier();
;     const char* SA = shm + (i & 3) * 32768; const char* SB = SA + 16384;
;     bf16x8 At[8], Bt[4];
; #pragma unroll
;     for (int n = 0; n < 4; ++n) { const int rb = wc * 64 + n * 16 + fr; Bt[n] = *reinterpret_cast<const bf16x8*>(SB + rb * 64 + ((fq ^ ((rb >> 2) & 3)) * 16)); }
; #pragma unroll
;     for (int m = 0; m < 8; ++m) { const int ra = wr * 128 + m * 16 + fr; At[m] = *reinterpret_cast<const bf16x8*>(SA + ra * 64 + ((fq ^ ((ra >> 2) & 3)) * 16)); }
;     if (i + 3 < nk) stage(i + 3);
; #pragma unroll
;     for (int m = 0; m < 8; ++m)
; #pragma unroll
;       for (int n = 0; n < 4; ++n) acc[m][n] = __builtin_amdgcn_mfma_f32_16x16x32_bf16(Bt[n], At[m], acc[m][n], 0, 0, 0);
;   }
;   __syncthreads();
	v_add3_u32 v231, v183, v151, s5
	v_add3_u32 v230, v183, v153, s5
	s_nop 0
	ds_read_b128 v[196:199], v231 offset:16384
	ds_read_b128 v[200:203], v231 offset:17408
	ds_read_b128 v[214:217], v231 offset:18432
	ds_read_b128 v[218:221], v231 offset:19456
	ds_read_b128 v[204:207], v230
	ds_read_b128 v[210:213], v230 offset:1024
	v_mfma_f32_16x16x32_bf16 v[28:31], v[232:235], v[248:251], v[28:31]
	v_mfma_f32_16x16x32_bf16 v[24:27], v[236:239], v[248:251], v[24:27]
	v_mfma_f32_16x16x32_bf16 v[20:23], v[240:243], v[248:251], v[20:23]
	v_mfma_f32_16x16x32_bf16 v[16:19], v[244:247], v[248:251], v[16:19]
	v_mfma_f32_16x16x32_bf16 v[12:15], v[232:235], v[222:225], v[12:15]
	v_mfma_f32_16x16x32_bf16 v[8:11], v[236:239], v[222:225], v[8:11]
	v_mfma_f32_16x16x32_bf16 v[4:7], v[240:243], v[222:225], v[4:7]
	v_mfma_f32_16x16x32_bf16 v[0:3], v[244:247], v[222:225], v[0:3]
	ds_read_b128 v[248:251], v230 offset:2048
	ds_read_b128 v[222:225], v230 offset:3072
	s_waitcnt lgkmcnt(2)
	v_mfma_f32_16x16x32_bf16 v[124:127], v[196:199], v[204:207], v[124:127]
	v_mfma_f32_16x16x32_bf16 v[120:123], v[200:203], v[204:207], v[120:123]
	v_mfma_f32_16x16x32_bf16 v[116:119], v[214:217], v[204:207], v[116:119]
	v_mfma_f32_16x16x32_bf16 v[112:115], v[218:221], v[204:207], v[112:115]
	v_mfma_f32_16x16x32_bf16 v[108:111], v[196:199], v[210:213], v[108:111]
	v_mfma_f32_16x16x32_bf16 v[104:107], v[200:203], v[210:213], v[104:107]
	v_mfma_f32_16x16x32_bf16 v[100:103], v[214:217], v[210:213], v[100:103]
	v_mfma_f32_16x16x32_bf16 v[96:99], v[218:221], v[210:213], v[96:99]
	ds_read_b128 v[204:207], v230 offset:4096
	ds_read_b128 v[210:213], v230 offset:5120
	s_waitcnt lgkmcnt(2)
	v_mfma_f32_16x16x32_bf16 v[92:95], v[196:199], v[248:251], v[92:95]
	v_mfma_f32_16x16x32_bf16 v[88:91], v[200:203], v[248:251], v[88:91]
	v_mfma_f32_16x16x32_bf16 v[84:87], v[214:217], v[248:251], v[84:87]
	v_mfma_f32_16x16x32_bf16 v[80:83], v[218:221], v[248:251], v[80:83]
	v_mfma_f32_16x16x32_bf16 v[76:79], v[196:199], v[222:225], v[76:79]
	v_mfma_f32_16x16x32_bf16 v[72:75], v[200:203], v[222:225], v[72:75]
	v_mfma_f32_16x16x32_bf16 v[68:71], v[214:217], v[222:225], v[68:71]
	v_mfma_f32_16x16x32_bf16 v[64:67], v[218:221], v[222:225], v[64:67]
	ds_read_b128 v[248:251], v230 offset:6144
	ds_read_b128 v[222:225], v230 offset:7168
	s_waitcnt lgkmcnt(2)
	v_mfma_f32_16x16x32_bf16 v[60:63], v[196:199], v[204:207], v[60:63]
	v_mfma_f32_16x16x32_bf16 v[56:59], v[200:203], v[204:207], v[56:59]
	v_mfma_f32_16x16x32_bf16 v[52:55], v[214:217], v[204:207], v[52:55]
	v_mfma_f32_16x16x32_bf16 v[48:51], v[218:221], v[204:207], v[48:51]
	v_mfma_f32_16x16x32_bf16 v[44:47], v[196:199], v[210:213], v[44:47]
	v_mfma_f32_16x16x32_bf16 v[40:43], v[200:203], v[210:213], v[40:43]
	v_mfma_f32_16x16x32_bf16 v[36:39], v[214:217], v[210:213], v[36:39]
	v_mfma_f32_16x16x32_bf16 v[32:35], v[218:221], v[210:213], v[32:35]
	s_add_i32 s5, s5, 0x8000
	s_and_b32 s5, s5, 0x18000
	s_waitcnt vmcnt(0) lgkmcnt(0)
	s_barrier
	v_add3_u32 v231, v183, v151, s5
	v_add3_u32 v230, v183, v153, s5
	s_nop 0
	ds_read_b128 v[232:235], v231 offset:16384
	ds_read_b128 v[236:239], v231 offset:17408
	ds_read_b128 v[240:243], v231 offset:18432
	ds_read_b128 v[244:247], v231 offset:19456
	ds_read_b128 v[204:207], v230
	ds_read_b128 v[210:213], v230 offset:1024
	v_mfma_f32_16x16x32_bf16 v[28:31], v[196:199], v[248:251], v[28:31]
	v_mfma_f32_16x16x32_bf16 v[24:27], v[200:203], v[248:251], v[24:27]
	v_mfma_f32_16x16x32_bf16 v[20:23], v[214:217], v[248:251], v[20:23]
	v_mfma_f32_16x16x32_bf16 v[16:19], v[218:221], v[248:251], v[16:19]
	v_mfma_f32_16x16x32_bf16 v[12:15], v[196:199], v[222:225], v[12:15]
	v_mfma_f32_16x16x32_bf16 v[8:11], v[200:203], v[222:225], v[8:11]
	v_mfma_f32_16x16x32_bf16 v[4:7], v[214:217], v[222:225], v[4:7]
	v_mfma_f32_16x16x32_bf16 v[0:3], v[218:221], v[222:225], v[0:3]
	ds_read_b128 v[248:251], v230 offset:2048
	ds_read_b128 v[222:225], v230 offset:3072
	s_waitcnt lgkmcnt(2)
	v_mfma_f32_16x16x32_bf16 v[124:127], v[232:235], v[204:207], v[124:127]
	v_mfma_f32_16x16x32_bf16 v[120:123], v[236:239], v[204:207], v[120:123]
	v_mfma_f32_16x16x32_bf16 v[116:119], v[240:243], v[204:207], v[116:119]
	v_mfma_f32_16x16x32_bf16 v[112:115], v[244:247], v[204:207], v[112:115]
	v_mfma_f32_16x16x32_bf16 v[108:111], v[232:235], v[210:213], v[108:111]
	v_mfma_f32_16x16x32_bf16 v[104:107], v[236:239], v[210:213], v[104:107]
	v_mfma_f32_16x16x32_bf16 v[100:103], v[240:243], v[210:213], v[100:103]
	v_mfma_f32_16x16x32_bf16 v[96:99], v[244:247], v[210:213], v[96:99]
	ds_read_b128 v[204:207], v230 offset:4096
	ds_read_b128 v[210:213], v230 offset:5120
	s_waitcnt lgkmcnt(2)
	v_mfma_f32_16x16x32_bf16 v[92:95], v[232:235], v[248:251], v[92:95]
	v_mfma_f32_16x16x32_bf16 v[88:91], v[236:239], v[248:251], v[88:91]
	v_mfma_f32_16x16x32_bf16 v[84:87], v[240:243], v[248:251], v[84:87]
	v_mfma_f32_16x16x32_bf16 v[80:83], v[244:247], v[248:251], v[80:83]
	v_mfma_f32_16x16x32_bf16 v[76:79], v[232:235], v[222:225], v[76:79]
	v_mfma_f32_16x16x32_bf16 v[72:75], v[236:239], v[222:225], v[72:75]
	v_mfma_f32_16x16x32_bf16 v[68:71], v[240:243], v[222:225], v[68:71]
	v_mfma_f32_16x16x32_bf16 v[64:67], v[244:247], v[222:225], v[64:67]
	ds_read_b128 v[248:251], v230 offset:6144
	ds_read_b128 v[222:225], v230 offset:7168
	s_waitcnt lgkmcnt(2)
	v_mfma_f32_16x16x32_bf16 v[60:63], v[232:235], v[204:207], v[60:63]
	v_mfma_f32_16x16x32_bf16 v[56:59], v[236:239], v[204:207], v[56:59]
	v_mfma_f32_16x16x32_bf16 v[52:55], v[240:243], v[204:207], v[52:55]
	v_mfma_f32_16x16x32_bf16 v[48:51], v[244:247], v[204:207], v[48:51]
	v_mfma_f32_16x16x32_bf16 v[44:47], v[232:235], v[210:213], v[44:47]
	v_mfma_f32_16x16x32_bf16 v[40:43], v[236:239], v[210:213], v[40:43]
	v_mfma_f32_16x16x32_bf16 v[36:39], v[240:243], v[210:213], v[36:39]
	v_mfma_f32_16x16x32_bf16 v[32:35], v[244:247], v[210:213], v[32:35]
	s_waitcnt lgkmcnt(0)
	v_mfma_f32_16x16x32_bf16 v[28:31], v[232:235], v[248:251], v[28:31]
	v_mfma_f32_16x16x32_bf16 v[24:27], v[236:239], v[248:251], v[24:27]
	v_mfma_f32_16x16x32_bf16 v[20:23], v[240:243], v[248:251], v[20:23]
	v_mfma_f32_16x16x32_bf16 v[16:19], v[244:247], v[248:251], v[16:19]
	v_mfma_f32_16x16x32_bf16 v[12:15], v[232:235], v[222:225], v[12:15]
	v_mfma_f32_16x16x32_bf16 v[8:11], v[236:239], v[222:225], v[8:11]
	v_mfma_f32_16x16x32_bf16 v[4:7], v[240:243], v[222:225], v[4:7]
	v_mfma_f32_16x16x32_bf16 v[0:3], v[244:247], v[222:225], v[0:3]
	s_nop 7
	s_nop 3
	s_add_i32 s15, s15, s9
	s_add_i32 s4, s4, s14
	s_cmp_lt_i32 s15, 64
	s_waitcnt vmcnt(0) lgkmcnt(0)
	s_barrier
; template <class Epi>
; DI void gemm_tile256(const u16* __restrict__ Ag, long lda, const u16* __restrict__ Bg, long ldb, int nk, char* shm, Epi&& epi) {
;     ...
;   __syncthreads();
; #pragma unroll
;   for (int m = 0; m < 8; ++m)
; #pragma unroll
;     for (int n = 0; n < 4; ++n) epi(wr * 128 + m * 16 + fr, wc * 64 + n * 16 + fq * 4, acc[m][n]);
; DI void phase6(const Params& P, char* smem) {
;     ...
;     gemm_tile256(cat + (long)brow * 1024, 1024, WoT + (long)bcol * 1024, 1024, 32, smem, [&](int row, int col0, f32x4 v) {
;       const long o = (long)(brow + row) * 1024 + bcol + col0;
;       const float4 xs = *reinterpret_cast<const float4*>(P.x + o);
;       *reinterpret_cast<float4*>(Z1 + o) = make_float4(ALPHA * xs.x + v[0], ALPHA * xs.y + v[1], ALPHA * xs.z + v[2], ALPHA * xs.w + v[3]);
;     });
	v_add_u32_e32 v164, s10, v155
	v_ashrrev_i32_e32 v165, 31, v164
	v_lshlrev_b64 v[196:197], 10, v[164:165]
	v_or_b32_e32 v164, v196, v148
	v_mov_b32_e32 v165, v197
	v_lshlrev_b64 v[164:165], 2, v[164:165]
	v_lshl_add_u64 v[198:199], s[52:53], 0, v[164:165]
	v_lshl_add_u64 v[200:201], s[38:39], 0, v[164:165]
	global_load_dwordx4 v[164:167], v[198:199], off
	s_waitcnt vmcnt(0)
	s_nop 4
	v_pk_fma_f32 v[124:125], v[164:165], s[6:7], v[124:125] op_sel_hi:[1,0,1]
	v_pk_fma_f32 v[126:127], v[166:167], s[6:7], v[126:127] op_sel_hi:[1,0,1]
	global_store_dwordx4 v[200:201], v[124:127], off
	s_nop 0
	v_or_b32_e32 v124, v196, v150
	v_mov_b32_e32 v125, v197
	v_lshl_add_u64 v[164:165], v[124:125], 2, s[38:39]
	global_load_dwordx4 v[124:127], v[198:199], off offset:64
	s_waitcnt vmcnt(0)
	v_pk_fma_f32 v[120:121], v[124:125], s[6:7], v[120:121] op_sel_hi:[1,0,1]
	v_pk_fma_f32 v[122:123], v[126:127], s[6:7], v[122:123] op_sel_hi:[1,0,1]
	global_store_dwordx4 v[164:165], v[120:123], off
	s_nop 0
	v_or_b32_e32 v120, v196, v152
	v_mov_b32_e32 v121, v197
	v_lshl_add_u64 v[124:125], v[120:121], 2, s[38:39]
	global_load_dwordx4 v[120:123], v[198:199], off offset:128
	v_or_b32_e32 v196, v196, v154
	s_waitcnt vmcnt(0)
	v_pk_fma_f32 v[116:117], v[120:121], s[6:7], v[116:117] op_sel_hi:[1,0,1]
	v_pk_fma_f32 v[118:119], v[122:123], s[6:7], v[118:119] op_sel_hi:[1,0,1]
	global_store_dwordx4 v[124:125], v[116:119], off
	global_load_dwordx4 v[116:119], v[198:199], off offset:192
	v_lshl_add_u64 v[120:121], v[196:197], 2, s[38:39]
	s_waitcnt vmcnt(0)
	v_pk_fma_f32 v[112:113], v[116:117], s[6:7], v[112:113] op_sel_hi:[1,0,1]
	v_pk_fma_f32 v[114:115], v[118:119], s[6:7], v[114:115] op_sel_hi:[1,0,1]
	global_store_dwordx4 v[120:121], v[112:115], off
	s_nop 0
	v_add_u32_e32 v112, s10, v176
	v_ashrrev_i32_e32 v113, 31, v112
	v_lshlrev_b64 v[116:117], 10, v[112:113]
	v_or_b32_e32 v112, v116, v148
	v_mov_b32_e32 v113, v117
	v_lshlrev_b64 v[112:113], 2, v[112:113]
	v_lshl_add_u64 v[118:119], s[52:53], 0, v[112:113]
	v_lshl_add_u64 v[120:121], s[38:39], 0, v[112:113]
	global_load_dwordx4 v[112:115], v[118:119], off
	s_waitcnt vmcnt(0)
	v_pk_fma_f32 v[108:109], v[112:113], s[6:7], v[108:109] op_sel_hi:[1,0,1]
	v_pk_fma_f32 v[110:111], v[114:115], s[6:7], v[110:111] op_sel_hi:[1,0,1]
	global_store_dwordx4 v[120:121], v[108:111], off
	s_nop 0
	v_or_b32_e32 v108, v116, v150
	v_mov_b32_e32 v109, v117
	v_lshl_add_u64 v[112:113], v[108:109], 2, s[38:39]
	global_load_dwordx4 v[108:111], v[118:119], off offset:64
	s_waitcnt vmcnt(0)
	v_pk_fma_f32 v[104:105], v[108:109], s[6:7], v[104:105] op_sel_hi:[1,0,1]
	v_pk_fma_f32 v[106:107], v[110:111], s[6:7], v[106:107] op_sel_hi:[1,0,1]
	global_store_dwordx4 v[112:113], v[104:107], off
	s_nop 0
	v_or_b32_e32 v104, v116, v152
	v_mov_b32_e32 v105, v117
	v_lshl_add_u64 v[108:109], v[104:105], 2, s[38:39]
	global_load_dwordx4 v[104:107], v[118:119], off offset:128
	v_or_b32_e32 v116, v116, v154
	s_waitcnt vmcnt(0)
	v_pk_fma_f32 v[100:101], v[104:105], s[6:7], v[100:101] op_sel_hi:[1,0,1]
	v_pk_fma_f32 v[102:103], v[106:107], s[6:7], v[102:103] op_sel_hi:[1,0,1]
	global_store_dwordx4 v[108:109], v[100:103], off
	global_load_dwordx4 v[100:103], v[118:119], off offset:192
	v_lshl_add_u64 v[104:105], v[116:117], 2, s[38:39]
	s_waitcnt vmcnt(0)
	v_pk_fma_f32 v[96:97], v[100:101], s[6:7], v[96:97] op_sel_hi:[1,0,1]
	v_pk_fma_f32 v[98:99], v[102:103], s[6:7], v[98:99] op_sel_hi:[1,0,1]
	global_store_dwordx4 v[104:105], v[96:99], off
	s_nop 0
	v_add_u32_e32 v96, s10, v177
	v_ashrrev_i32_e32 v97, 31, v96
	v_lshlrev_b64 v[100:101], 10, v[96:97]
	v_or_b32_e32 v96, v100, v148
	v_mov_b32_e32 v97, v101
	v_lshlrev_b64 v[96:97], 2, v[96:97]
	v_lshl_add_u64 v[102:103], s[52:53], 0, v[96:97]
	v_lshl_add_u64 v[104:105], s[38:39], 0, v[96:97]
	global_load_dwordx4 v[96:99], v[102:103], off
	s_waitcnt vmcnt(0)
	v_pk_fma_f32 v[92:93], v[96:97], s[6:7], v[92:93] op_sel_hi:[1,0,1]
	v_pk_fma_f32 v[94:95], v[98:99], s[6:7], v[94:95] op_sel_hi:[1,0,1]
	global_store_dwordx4 v[104:105], v[92:95], off
	s_nop 0
	v_or_b32_e32 v92, v100, v150
	v_mov_b32_e32 v93, v101
	v_lshl_add_u64 v[96:97], v[92:93], 2, s[38:39]
	global_load_dwordx4 v[92:95], v[102:103], off offset:64
	s_waitcnt vmcnt(0)
	v_pk_fma_f32 v[88:89], v[92:93], s[6:7], v[88:89] op_sel_hi:[1,0,1]
	v_pk_fma_f32 v[90:91], v[94:95], s[6:7], v[90:91] op_sel_hi:[1,0,1]
	global_store_dwordx4 v[96:97], v[88:91], off
	s_nop 0
	v_or_b32_e32 v88, v100, v152
	v_mov_b32_e32 v89, v101
	v_lshl_add_u64 v[92:93], v[88:89], 2, s[38:39]
	global_load_dwordx4 v[88:91], v[102:103], off offset:128
	v_or_b32_e32 v100, v100, v154
	s_waitcnt vmcnt(0)
	v_pk_fma_f32 v[84:85], v[88:89], s[6:7], v[84:85] op_sel_hi:[1,0,1]
	v_pk_fma_f32 v[86:87], v[90:91], s[6:7], v[86:87] op_sel_hi:[1,0,1]
	global_store_dwordx4 v[92:93], v[84:87], off
	global_load_dwordx4 v[84:87], v[102:103], off offset:192
	v_lshl_add_u64 v[88:89], v[100:101], 2, s[38:39]
	s_waitcnt vmcnt(0)
	v_pk_fma_f32 v[80:81], v[84:85], s[6:7], v[80:81] op_sel_hi:[1,0,1]
	v_pk_fma_f32 v[82:83], v[86:87], s[6:7], v[82:83] op_sel_hi:[1,0,1]
	global_store_dwordx4 v[88:89], v[80:83], off
	s_nop 1
	v_add_u32_e32 v80, s10, v178
	v_ashrrev_i32_e32 v81, 31, v80
	v_lshlrev_b64 v[84:85], 10, v[80:81]
	v_or_b32_e32 v80, v84, v148
	v_mov_b32_e32 v81, v85
	v_lshlrev_b64 v[80:81], 2, v[80:81]
	v_lshl_add_u64 v[86:87], s[52:53], 0, v[80:81]
	v_lshl_add_u64 v[88:89], s[38:39], 0, v[80:81]
	global_load_dwordx4 v[80:83], v[86:87], off
	s_waitcnt vmcnt(0)
; template <class Epi>
; DI void gemm_tile256(const u16* __restrict__ Ag, long lda, const u16* __restrict__ Bg, long ldb, int nk, char* shm, Epi&& epi) {
;     ...
;   for (int m = 0; m < 8; ++m)
; #pragma unroll
;     for (int n = 0; n < 4; ++n) epi(wr * 128 + m * 16 + fr, wc * 64 + n * 16 + fq * 4, acc[m][n]);
; DI void phase6(const Params& P, char* smem) {
;     ...
;       const long o = (long)(brow + row) * 1024 + bcol + col0;
;       const float4 xs = *reinterpret_cast<const float4*>(P.x + o);
;       *reinterpret_cast<float4*>(Z1 + o) = make_float4(ALPHA * xs.x + v[0], ALPHA * xs.y + v[1], ALPHA * xs.z + v[2], ALPHA * xs.w + v[3]);
;     });
	v_pk_fma_f32 v[76:77], v[80:81], s[6:7], v[76:77] op_sel_hi:[1,0,1]
	v_pk_fma_f32 v[78:79], v[82:83], s[6:7], v[78:79] op_sel_hi:[1,0,1]
	global_store_dwordx4 v[88:89], v[76:79], off
	s_nop 1
	v_or_b32_e32 v76, v84, v150
	v_mov_b32_e32 v77, v85
	v_lshl_add_u64 v[80:81], v[76:77], 2, s[38:39]
	global_load_dwordx4 v[76:79], v[86:87], off offset:64
	s_waitcnt vmcnt(0)
	v_pk_fma_f32 v[72:73], v[76:77], s[6:7], v[72:73] op_sel_hi:[1,0,1]
	v_pk_fma_f32 v[74:75], v[78:79], s[6:7], v[74:75] op_sel_hi:[1,0,1]
	global_store_dwordx4 v[80:81], v[72:75], off
	s_nop 1
	v_or_b32_e32 v72, v84, v152
	v_mov_b32_e32 v73, v85
	v_lshl_add_u64 v[76:77], v[72:73], 2, s[38:39]
	global_load_dwordx4 v[72:75], v[86:87], off offset:128
	v_or_b32_e32 v84, v84, v154
	s_waitcnt vmcnt(0)
	v_pk_fma_f32 v[68:69], v[72:73], s[6:7], v[68:69] op_sel_hi:[1,0,1]
	v_pk_fma_f32 v[70:71], v[74:75], s[6:7], v[70:71] op_sel_hi:[1,0,1]
	global_store_dwordx4 v[76:77], v[68:71], off
	global_load_dwordx4 v[68:71], v[86:87], off offset:192
	v_lshl_add_u64 v[72:73], v[84:85], 2, s[38:39]
	s_waitcnt vmcnt(0)
	v_pk_fma_f32 v[64:65], v[68:69], s[6:7], v[64:65] op_sel_hi:[1,0,1]
	v_pk_fma_f32 v[66:67], v[70:71], s[6:7], v[66:67] op_sel_hi:[1,0,1]
	global_store_dwordx4 v[72:73], v[64:67], off
	s_nop 1
	v_add_u32_e32 v64, s10, v179
	v_ashrrev_i32_e32 v65, 31, v64
	v_lshlrev_b64 v[68:69], 10, v[64:65]
	v_or_b32_e32 v64, v68, v148
	v_mov_b32_e32 v65, v69
	v_lshlrev_b64 v[64:65], 2, v[64:65]
	v_lshl_add_u64 v[70:71], s[52:53], 0, v[64:65]
	v_lshl_add_u64 v[72:73], s[38:39], 0, v[64:65]
	global_load_dwordx4 v[64:67], v[70:71], off
	s_waitcnt vmcnt(0)
	v_pk_fma_f32 v[60:61], v[64:65], s[6:7], v[60:61] op_sel_hi:[1,0,1]
	v_pk_fma_f32 v[62:63], v[66:67], s[6:7], v[62:63] op_sel_hi:[1,0,1]
	global_store_dwordx4 v[72:73], v[60:63], off
	s_nop 1
	v_or_b32_e32 v60, v68, v150
	v_mov_b32_e32 v61, v69
	v_lshl_add_u64 v[64:65], v[60:61], 2, s[38:39]
	global_load_dwordx4 v[60:63], v[70:71], off offset:64
	s_waitcnt vmcnt(0)
	v_pk_fma_f32 v[56:57], v[60:61], s[6:7], v[56:57] op_sel_hi:[1,0,1]
	v_pk_fma_f32 v[58:59], v[62:63], s[6:7], v[58:59] op_sel_hi:[1,0,1]
	global_store_dwordx4 v[64:65], v[56:59], off
	s_nop 1
	v_or_b32_e32 v56, v68, v152
	v_mov_b32_e32 v57, v69
	v_lshl_add_u64 v[60:61], v[56:57], 2, s[38:39]
	global_load_dwordx4 v[56:59], v[70:71], off offset:128
	v_or_b32_e32 v68, v68, v154
	s_waitcnt vmcnt(0)
	v_pk_fma_f32 v[52:53], v[56:57], s[6:7], v[52:53] op_sel_hi:[1,0,1]
	v_pk_fma_f32 v[54:55], v[58:59], s[6:7], v[54:55] op_sel_hi:[1,0,1]
	global_store_dwordx4 v[60:61], v[52:55], off
	global_load_dwordx4 v[52:55], v[70:71], off offset:192
	v_lshl_add_u64 v[56:57], v[68:69], 2, s[38:39]
	s_waitcnt vmcnt(0)
	v_pk_fma_f32 v[48:49], v[52:53], s[6:7], v[48:49] op_sel_hi:[1,0,1]
	v_pk_fma_f32 v[50:51], v[54:55], s[6:7], v[50:51] op_sel_hi:[1,0,1]
	global_store_dwordx4 v[56:57], v[48:51], off
	s_nop 1
	v_add_u32_e32 v48, s10, v180
	v_ashrrev_i32_e32 v49, 31, v48
	v_lshlrev_b64 v[52:53], 10, v[48:49]
	v_or_b32_e32 v48, v52, v148
	v_mov_b32_e32 v49, v53
	v_lshlrev_b64 v[48:49], 2, v[48:49]
	v_lshl_add_u64 v[54:55], s[52:53], 0, v[48:49]
	v_lshl_add_u64 v[56:57], s[38:39], 0, v[48:49]
	global_load_dwordx4 v[48:51], v[54:55], off
	s_waitcnt vmcnt(0)
	v_pk_fma_f32 v[44:45], v[48:49], s[6:7], v[44:45] op_sel_hi:[1,0,1]
	v_pk_fma_f32 v[46:47], v[50:51], s[6:7], v[46:47] op_sel_hi:[1,0,1]
	global_store_dwordx4 v[56:57], v[44:47], off
	s_nop 1
	v_or_b32_e32 v44, v52, v150
	v_mov_b32_e32 v45, v53
	v_lshl_add_u64 v[48:49], v[44:45], 2, s[38:39]
	global_load_dwordx4 v[44:47], v[54:55], off offset:64
	s_waitcnt vmcnt(0)
	v_pk_fma_f32 v[40:41], v[44:45], s[6:7], v[40:41] op_sel_hi:[1,0,1]
	v_pk_fma_f32 v[42:43], v[46:47], s[6:7], v[42:43] op_sel_hi:[1,0,1]
	global_store_dwordx4 v[48:49], v[40:43], off
	s_nop 1
	v_or_b32_e32 v40, v52, v152
	v_mov_b32_e32 v41, v53
	v_lshl_add_u64 v[44:45], v[40:41], 2, s[38:39]
	global_load_dwordx4 v[40:43], v[54:55], off offset:128
	v_or_b32_e32 v52, v52, v154
	s_waitcnt vmcnt(0)
; template <class Epi>
; DI void gemm_tile256(const u16* __restrict__ Ag, long lda, const u16* __restrict__ Bg, long ldb, int nk, char* shm, Epi&& epi) {
;     ...
;   for (int m = 0; m < 8; ++m)
; #pragma unroll
;     for (int n = 0; n < 4; ++n) epi(wr * 128 + m * 16 + fr, wc * 64 + n * 16 + fq * 4, acc[m][n]);
; DI void phase6(const Params& P, char* smem) {
;     ...
;   for (int q = RBLK >> 3; q < 64; q += RGRID >> 3) {
;     const int brow = (q * 2 + ((RBLK & 7) >> 2)) * 256, bcol = (RBLK & 3) * 256;
;     gemm_tile256(cat + (long)brow * 1024, 1024, WoT + (long)bcol * 1024, 1024, 32, smem, [&](int row, int col0, f32x4 v) {
;       const long o = (long)(brow + row) * 1024 + bcol + col0;
;       const float4 xs = *reinterpret_cast<const float4*>(P.x + o);
;       *reinterpret_cast<float4*>(Z1 + o) = make_float4(ALPHA * xs.x + v[0], ALPHA * xs.y + v[1], ALPHA * xs.z + v[2], ALPHA * xs.w + v[3]);
;     });
	v_pk_fma_f32 v[36:37], v[40:41], s[6:7], v[36:37] op_sel_hi:[1,0,1]
	v_pk_fma_f32 v[38:39], v[42:43], s[6:7], v[38:39] op_sel_hi:[1,0,1]
	global_store_dwordx4 v[44:45], v[36:39], off
	global_load_dwordx4 v[36:39], v[54:55], off offset:192
	v_lshl_add_u64 v[40:41], v[52:53], 2, s[38:39]
	s_waitcnt vmcnt(0)
	v_pk_fma_f32 v[32:33], v[36:37], s[6:7], v[32:33] op_sel_hi:[1,0,1]
	v_pk_fma_f32 v[34:35], v[38:39], s[6:7], v[34:35] op_sel_hi:[1,0,1]
	global_store_dwordx4 v[40:41], v[32:35], off
	s_nop 1
	v_add_u32_e32 v32, s10, v181
	v_ashrrev_i32_e32 v33, 31, v32
	v_lshlrev_b64 v[36:37], 10, v[32:33]
	v_or_b32_e32 v32, v36, v148
	v_mov_b32_e32 v33, v37
	v_lshlrev_b64 v[32:33], 2, v[32:33]
	v_lshl_add_u64 v[38:39], s[52:53], 0, v[32:33]
	v_lshl_add_u64 v[40:41], s[38:39], 0, v[32:33]
	global_load_dwordx4 v[32:35], v[38:39], off
	s_waitcnt vmcnt(0)
	v_pk_fma_f32 v[28:29], v[32:33], s[6:7], v[28:29] op_sel_hi:[1,0,1]
	v_pk_fma_f32 v[30:31], v[34:35], s[6:7], v[30:31] op_sel_hi:[1,0,1]
	global_store_dwordx4 v[40:41], v[28:31], off
	s_nop 1
	v_or_b32_e32 v28, v36, v150
	v_mov_b32_e32 v29, v37
	v_lshl_add_u64 v[32:33], v[28:29], 2, s[38:39]
	global_load_dwordx4 v[28:31], v[38:39], off offset:64
	s_waitcnt vmcnt(0)
	v_pk_fma_f32 v[24:25], v[28:29], s[6:7], v[24:25] op_sel_hi:[1,0,1]
	v_pk_fma_f32 v[26:27], v[30:31], s[6:7], v[26:27] op_sel_hi:[1,0,1]
	global_store_dwordx4 v[32:33], v[24:27], off
	s_nop 1
	v_or_b32_e32 v24, v36, v152
	v_mov_b32_e32 v25, v37
	v_lshl_add_u64 v[28:29], v[24:25], 2, s[38:39]
	global_load_dwordx4 v[24:27], v[38:39], off offset:128
	v_or_b32_e32 v36, v36, v154
	s_waitcnt vmcnt(0)
	v_pk_fma_f32 v[20:21], v[24:25], s[6:7], v[20:21] op_sel_hi:[1,0,1]
	v_pk_fma_f32 v[22:23], v[26:27], s[6:7], v[22:23] op_sel_hi:[1,0,1]
	global_store_dwordx4 v[28:29], v[20:23], off
	global_load_dwordx4 v[20:23], v[38:39], off offset:192
	v_lshl_add_u64 v[24:25], v[36:37], 2, s[38:39]
	s_waitcnt vmcnt(0)
	v_pk_fma_f32 v[16:17], v[20:21], s[6:7], v[16:17] op_sel_hi:[1,0,1]
	v_pk_fma_f32 v[18:19], v[22:23], s[6:7], v[18:19] op_sel_hi:[1,0,1]
	global_store_dwordx4 v[24:25], v[16:19], off
	s_nop 1
	v_add_u32_e32 v16, s10, v182
	v_ashrrev_i32_e32 v17, 31, v16
	v_lshlrev_b64 v[20:21], 10, v[16:17]
	v_or_b32_e32 v16, v20, v148
	v_mov_b32_e32 v17, v21
	v_lshlrev_b64 v[16:17], 2, v[16:17]
	v_lshl_add_u64 v[22:23], s[52:53], 0, v[16:17]
	v_lshl_add_u64 v[24:25], s[38:39], 0, v[16:17]
	global_load_dwordx4 v[16:19], v[22:23], off
	s_waitcnt vmcnt(0)
	v_pk_fma_f32 v[12:13], v[16:17], s[6:7], v[12:13] op_sel_hi:[1,0,1]
	v_pk_fma_f32 v[14:15], v[18:19], s[6:7], v[14:15] op_sel_hi:[1,0,1]
	global_store_dwordx4 v[24:25], v[12:15], off
	s_nop 1
	v_or_b32_e32 v12, v20, v150
	v_mov_b32_e32 v13, v21
	v_lshl_add_u64 v[16:17], v[12:13], 2, s[38:39]
	global_load_dwordx4 v[12:15], v[22:23], off offset:64
	s_waitcnt vmcnt(0)
	v_pk_fma_f32 v[8:9], v[12:13], s[6:7], v[8:9] op_sel_hi:[1,0,1]
	v_pk_fma_f32 v[10:11], v[14:15], s[6:7], v[10:11] op_sel_hi:[1,0,1]
	global_store_dwordx4 v[16:17], v[8:11], off
	s_nop 1
	v_or_b32_e32 v8, v20, v152
	v_mov_b32_e32 v9, v21
	v_lshl_add_u64 v[12:13], v[8:9], 2, s[38:39]
	global_load_dwordx4 v[8:11], v[22:23], off offset:128
	v_or_b32_e32 v20, v20, v154
	s_waitcnt vmcnt(0)
	v_pk_fma_f32 v[4:5], v[8:9], s[6:7], v[4:5] op_sel_hi:[1,0,1]
	v_pk_fma_f32 v[6:7], v[10:11], s[6:7], v[6:7] op_sel_hi:[1,0,1]
	global_store_dwordx4 v[12:13], v[4:7], off
	global_load_dwordx4 v[4:7], v[22:23], off offset:192
	v_lshl_add_u64 v[8:9], v[20:21], 2, s[38:39]
	s_waitcnt vmcnt(0)
	v_pk_fma_f32 v[0:1], v[4:5], s[6:7], v[0:1] op_sel_hi:[1,0,1]
	v_pk_fma_f32 v[2:3], v[6:7], s[6:7], v[2:3] op_sel_hi:[1,0,1]
	global_store_dwordx4 v[8:9], v[0:3], off
	s_cbranch_scc1 .LBB0_946

; template <class Epi>
; DI void gemm_tile256(const u16* __restrict__ Ag, long lda, const u16* __restrict__ Bg, long ldb, int nk, char* shm, Epi&& epi) {
;   const int tid = RTID, wid = tid >> 6, lane = tid & 63, wr = wid >> 2, wc = wid & 3, fr = lane & 15, fq = lane >> 4;
;   f32x4 acc[8][4];
; #pragma unroll
;   for (int m = 0; m < 8; ++m)
; #pragma unroll
;     for (int n = 0; n < 4; ++n) acc[m][n] = f32x4{0.f, 0.f, 0.f, 0.f};
;   const int q0 = tid, q1 = 512 + tid;
;   const int r0 = q0 >> 2, r1 = q1 >> 2, c0 = (q0 & 3) ^ ((r0 >> 2) & 3), c1 = (q1 & 3) ^ ((r1 >> 2) & 3);
;   const u16* a0 = Ag + (long)r0 * lda + c0 * 8; const u16* a1 = Ag + (long)r1 * lda + c1 * 8;
;   const u16* b0 = Bg + (long)r0 * ldb + c0 * 8; const u16* b1 = Bg + (long)r1 * ldb + c1 * 8;
;   auto stage = [&](int j) {
;     char* SA = shm + (j & 3) * 32768; char* SB = SA + 16384;
;     __builtin_amdgcn_global_load_lds((const unsigned*)(a0 + j * 32), (__attribute__((address_space(3))) unsigned*)(SA + q0 * 16), 16, 0, 0);
;     __builtin_amdgcn_global_load_lds((const unsigned*)(a1 + j * 32), (__attribute__((address_space(3))) unsigned*)(SA + q1 * 16), 16, 0, 0);
;     __builtin_amdgcn_global_load_lds((const unsigned*)(b0 + j * 32), (__attribute__((address_space(3))) unsigned*)(SB + q0 * 16), 16, 0, 0);
;     __builtin_amdgcn_global_load_lds((const unsigned*)(b1 + j * 32), (__attribute__((address_space(3))) unsigned*)(SB + q1 * 16), 16, 0, 0);
;   };
;   __syncthreads();
;   stage(0);
;   if (nk > 1) stage(1);
;   if (nk > 2) stage(2);
;   for (int i = 0; i < nk; ++i) {
;     if (i + 2 < nk) asm volatile("s_waitcnt vmcnt(8)" ::: "memory");
;     else if (i + 1 < nk) asm volatile("s_waitcnt vmcnt(4)" ::: "memory");
;     else asm volatile("s_waitcnt vmcnt(0)" ::: "memory");
;     __builtin_amdgcn_s_barrier();
;     const char* SA = shm + (i & 3) * 32768; const char* SB = SA + 16384;
; DI void phase8(const Params& P, char* smem) {
;     ...
;   for (int q = RBLK >> 3; q < 128; q += RGRID >> 3) {
;     const int brow = q * 256, bcol = (RBLK & 7) * 256;
;     gemm_tile256(h1b + (long)brow * 1024, 1024, WqT + (long)bcol * 1024, 1024, 32, smem, [&](int row, int col0, f32x4 v) {
.LBB0_1068:
	s_ashr_i32 s7, s6, 31
	s_lshl_b64 s[10:11], s[6:7], 11
	v_lshl_add_u64 v[158:159], v[150:151], 0, s[10:11]
	v_lshl_add_u64 v[160:161], v[152:153], 0, s[10:11]
	s_lshl_b32 s10, s75, 8
	s_ashr_i32 s11, s10, 31
	s_lshl_b64 s[12:13], s[10:11], 11
	s_add_u32 s12, s40, s12
	s_addc_u32 s13, s41, s13
	v_add_u32_e32 v6, 0, v209
	v_lshl_add_u64 v[0:1], s[12:13], 0, v[130:131]
	v_readfirstlane_b32 s7, v6
	v_add_u32_e32 v7, 0, v162
	v_lshl_add_u64 v[0:1], v[0:1], 0, v[132:133]
	v_lshl_add_u64 v[2:3], s[12:13], 0, v[134:135]
	s_mov_b32 m0, s7
	v_readfirstlane_b32 s7, v7
	v_add_u32_e32 v4, 0x4000, v6
	v_lshl_add_u64 v[2:3], v[2:3], 0, v[132:133]
	s_barrier
	global_load_lds_dwordx4 v[0:1], off
	s_mov_b32 m0, s7
	v_readfirstlane_b32 s7, v4
	v_add_u32_e32 v4, 0x4000, v7
	global_load_lds_dwordx4 v[2:3], off
	s_mov_b32 m0, s7
	v_readfirstlane_b32 s7, v4
	v_add_u32_e32 v8, 0x8000, v6
	global_load_lds_dwordx4 v[136:137], off
	s_mov_b32 m0, s7
	v_readfirstlane_b32 s7, v8
	v_add_u32_e32 v8, 0x8000, v7
	global_load_lds_dwordx4 v[138:139], off
	v_lshl_add_u64 v[4:5], v[0:1], 0, 64
	s_mov_b32 m0, s7
	v_readfirstlane_b32 s7, v8
	global_load_lds_dwordx4 v[4:5], off
	v_lshl_add_u64 v[4:5], v[2:3], 0, 64
	s_mov_b32 m0, s7
	v_lshl_add_u64 v[0:1], v[0:1], 0, s[0:1]
	global_load_lds_dwordx4 v[4:5], off
	v_add_u32_e32 v4, 0xc000, v6
	s_mov_b64 s[12:13], 0
	v_readfirstlane_b32 s7, v4
	v_add_u32_e32 v4, 0xc000, v7
	s_mov_b32 m0, s7
	v_readfirstlane_b32 s7, v4
	v_add_u32_e32 v4, s2, v209
	global_load_lds_dwordx4 v[140:141], off
	s_mov_b32 m0, s7
	v_readfirstlane_b32 s7, v4
	global_load_lds_dwordx4 v[142:143], off
	s_mov_b32 m0, s7
	v_mov_b32_e32 v4, 0
	global_load_lds_dwordx4 v[0:1], off
	v_lshl_add_u64 v[0:1], v[2:3], 0, s[0:1]
	v_add_u32_e32 v2, s2, v162
	v_mov_b32_e32 v3, v133
	v_readfirstlane_b32 s7, v2
	s_mov_b32 m0, s7
	v_mov_b32_e32 v2, v133
	global_load_lds_dwordx4 v[0:1], off
	v_add_u32_e32 v0, s4, v209
	v_mov_b32_e32 v1, v133
	v_readfirstlane_b32 s7, v0
	v_add_u32_e32 v0, s4, v162
	s_mov_b32 m0, s7
	v_readfirstlane_b32 s7, v0
	global_load_lds_dwordx4 v[144:145], off
	s_mov_b32 m0, s7
	s_mov_b32 s7, 0x18000
	global_load_lds_dwordx4 v[146:147], off
	v_mov_b32_e32 v0, 0
	v_mov_b32_e32 v5, v133
	v_mov_b32_e32 v6, v133
	v_mov_b32_e32 v7, v133
	v_mov_b32_e32 v8, 0
	v_mov_b32_e32 v9, v133
	v_mov_b32_e32 v10, v133
	v_mov_b32_e32 v11, v133
	v_mov_b32_e32 v12, 0
	v_mov_b32_e32 v13, v133
	v_mov_b32_e32 v14, v133
	v_mov_b32_e32 v15, v133
	v_mov_b32_e32 v16, 0
	v_mov_b32_e32 v17, v133
	v_mov_b32_e32 v18, v133
	v_mov_b32_e32 v19, v133
	v_mov_b32_e32 v20, 0
	v_mov_b32_e32 v21, v133
	v_mov_b32_e32 v22, v133
	v_mov_b32_e32 v23, v133
	v_mov_b32_e32 v24, 0
	v_mov_b32_e32 v25, v133
	v_mov_b32_e32 v26, v133
	v_mov_b32_e32 v27, v133
	v_mov_b32_e32 v28, 0
	v_mov_b32_e32 v29, v133
	v_mov_b32_e32 v30, v133
	v_mov_b32_e32 v31, v133
	v_mov_b32_e32 v32, 0
	v_mov_b32_e32 v33, v133
	v_mov_b32_e32 v34, v133
	v_mov_b32_e32 v35, v133
	v_mov_b32_e32 v36, 0
	v_mov_b32_e32 v37, v133
	v_mov_b32_e32 v38, v133
	v_mov_b32_e32 v39, v133
	v_mov_b32_e32 v40, 0
	v_mov_b32_e32 v41, v133
	v_mov_b32_e32 v42, v133
	v_mov_b32_e32 v43, v133
	v_mov_b32_e32 v44, 0
	v_mov_b32_e32 v45, v133
	v_mov_b32_e32 v46, v133
	v_mov_b32_e32 v47, v133
	v_mov_b32_e32 v48, 0
	v_mov_b32_e32 v49, v133
	v_mov_b32_e32 v50, v133
	v_mov_b32_e32 v51, v133
	v_mov_b32_e32 v52, 0
	v_mov_b32_e32 v53, v133
	v_mov_b32_e32 v54, v133
	v_mov_b32_e32 v55, v133
	v_mov_b32_e32 v56, 0
	v_mov_b32_e32 v57, v133
	v_mov_b32_e32 v58, v133
	v_mov_b32_e32 v59, v133
	v_mov_b32_e32 v60, 0
	v_mov_b32_e32 v61, v133
	v_mov_b32_e32 v62, v133
	v_mov_b32_e32 v63, v133
	v_mov_b32_e32 v64, 0
	v_mov_b32_e32 v65, v133
	v_mov_b32_e32 v66, v133
	v_mov_b32_e32 v67, v133
	v_mov_b32_e32 v68, 0
	v_mov_b32_e32 v69, v133
	v_mov_b32_e32 v70, v133
	v_mov_b32_e32 v71, v133
	v_mov_b32_e32 v72, 0
	v_mov_b32_e32 v73, v133
	v_mov_b32_e32 v74, v133
	v_mov_b32_e32 v75, v133
	v_mov_b32_e32 v76, 0
	v_mov_b32_e32 v77, v133
	v_mov_b32_e32 v78, v133
	v_mov_b32_e32 v79, v133
	v_mov_b32_e32 v80, 0
	v_mov_b32_e32 v81, v133
	v_mov_b32_e32 v82, v133
	v_mov_b32_e32 v83, v133
	v_mov_b32_e32 v84, 0
	v_mov_b32_e32 v85, v133
	v_mov_b32_e32 v86, v133
	v_mov_b32_e32 v87, v133
	v_mov_b32_e32 v88, 0
	v_mov_b32_e32 v89, v133
	v_mov_b32_e32 v90, v133
	v_mov_b32_e32 v91, v133
	v_mov_b32_e32 v92, 0
	v_mov_b32_e32 v93, v133
	v_mov_b32_e32 v94, v133
	v_mov_b32_e32 v95, v133
	v_mov_b32_e32 v96, 0
	v_mov_b32_e32 v97, v133
	v_mov_b32_e32 v98, v133
	v_mov_b32_e32 v99, v133
	v_mov_b32_e32 v100, 0
	v_mov_b32_e32 v101, v133
	v_mov_b32_e32 v102, v133
	v_mov_b32_e32 v103, v133
	v_mov_b32_e32 v104, 0
	v_mov_b32_e32 v105, v133
	v_mov_b32_e32 v106, v133
	v_mov_b32_e32 v107, v133
	v_mov_b32_e32 v108, 0
	v_mov_b32_e32 v109, v133
	v_mov_b32_e32 v110, v133
	v_mov_b32_e32 v111, v133
	v_mov_b32_e32 v112, 0
	v_mov_b32_e32 v113, v133
	v_mov_b32_e32 v114, v133
	v_mov_b32_e32 v115, v133
	v_mov_b32_e32 v116, 0
	v_mov_b32_e32 v117, v133
	v_mov_b32_e32 v118, v133
	v_mov_b32_e32 v119, v133
	v_mov_b32_e32 v120, 0
	v_mov_b32_e32 v121, v133
	v_mov_b32_e32 v122, v133
	v_mov_b32_e32 v123, v133
	v_mov_b32_e32 v124, 0
	v_mov_b32_e32 v125, v133
	v_mov_b32_e32 v126, v133
	v_mov_b32_e32 v127, v133
	v_readfirstlane_b32 s11, v209
	s_mov_b32 s7, 0
	s_mov_b64 s[12:13], 0
	s_waitcnt vmcnt(8)
	s_barrier
	v_add3_u32 v187, v181, v163, s7
	v_add3_u32 v186, v181, v164, s7
	s_nop 0
	ds_read_b128 v[194:197], v187 offset:16384
	ds_read_b128 v[198:201], v187 offset:17408
	ds_read_b128 v[216:219], v187 offset:18432
	ds_read_b128 v[220:223], v187 offset:19456
	ds_read_b128 v[202:205], v186
	ds_read_b128 v[212:215], v186 offset:1024
; template <class Epi>
; DI void gemm_tile256(const u16* __restrict__ Ag, long lda, const u16* __restrict__ Bg, long ldb, int nk, char* shm, Epi&& epi) {
;     ...
;   for (int i = 0; i < nk; ++i) {
;     if (i + 2 < nk) asm volatile("s_waitcnt vmcnt(8)" ::: "memory");
;     else if (i + 1 < nk) asm volatile("s_waitcnt vmcnt(4)" ::: "memory");
;     else asm volatile("s_waitcnt vmcnt(0)" ::: "memory");
;     __builtin_amdgcn_s_barrier();
;     const char* SA = shm + (i & 3) * 32768; const char* SB = SA + 16384;
;     bf16x8 At[8], Bt[4];
; #pragma unroll
;     for (int n = 0; n < 4; ++n) { const int rb = wc * 64 + n * 16 + fr; Bt[n] = *reinterpret_cast<const bf16x8*>(SB + rb * 64 + ((fq ^ ((rb >> 2) & 3)) * 16)); }
; #pragma unroll
;     for (int m = 0; m < 8; ++m) { const int ra = wr * 128 + m * 16 + fr; At[m] = *reinterpret_cast<const bf16x8*>(SA + ra * 64 + ((fq ^ ((ra >> 2) & 3)) * 16)); }
;     if (i + 3 < nk) stage(i + 3);
; #pragma unroll
;     for (int m = 0; m < 8; ++m)
; #pragma unroll
;       for (int n = 0; n < 4; ++n) acc[m][n] = __builtin_amdgcn_mfma_f32_16x16x32_bf16(Bt[n], At[m], acc[m][n], 0, 0, 0);
;   }
.Lgemm_p8_kloop:
	s_add_i32 s9, s7, 0x18000
	s_and_b32 s9, s9, 0x18000
	s_add_i32 s14, s9, s11
	ds_read_b128 v[246:249], v186 offset:2048
	ds_read_b128 v[250:253], v186 offset:3072
	s_waitcnt lgkmcnt(2)
	v_mfma_f32_16x16x32_bf16 v[124:127], v[194:197], v[202:205], v[124:127]
	v_lshl_add_u64 v[206:207], v[158:159], 0, s[12:13]
	v_mfma_f32_16x16x32_bf16 v[120:123], v[198:201], v[202:205], v[120:123]
	s_mov_b32 m0, s14
	v_mfma_f32_16x16x32_bf16 v[116:119], v[216:219], v[202:205], v[116:119]
	s_add_i32 s14, s14, 0x2000
	v_mfma_f32_16x16x32_bf16 v[112:115], v[220:223], v[202:205], v[112:115]
	global_load_lds_dwordx4 v[206:207], off
	v_mfma_f32_16x16x32_bf16 v[108:111], v[194:197], v[212:215], v[108:111]
	v_mfma_f32_16x16x32_bf16 v[104:107], v[198:201], v[212:215], v[104:107]
	v_mfma_f32_16x16x32_bf16 v[100:103], v[216:219], v[212:215], v[100:103]
	v_mfma_f32_16x16x32_bf16 v[96:99], v[220:223], v[212:215], v[96:99]
	ds_read_b128 v[202:205], v186 offset:4096
	ds_read_b128 v[212:215], v186 offset:5120
	s_waitcnt lgkmcnt(2)
	v_mfma_f32_16x16x32_bf16 v[92:95], v[194:197], v[246:249], v[92:95]
	v_lshl_add_u64 v[224:225], v[160:161], 0, s[12:13]
	v_mfma_f32_16x16x32_bf16 v[88:91], v[198:201], v[246:249], v[88:91]
	s_mov_b32 m0, s14
	v_mfma_f32_16x16x32_bf16 v[84:87], v[216:219], v[246:249], v[84:87]
	s_add_i32 s14, s14, 0x2000
	v_mfma_f32_16x16x32_bf16 v[80:83], v[220:223], v[246:249], v[80:83]
	global_load_lds_dwordx4 v[224:225], off
	v_mfma_f32_16x16x32_bf16 v[76:79], v[194:197], v[250:253], v[76:79]
	v_mfma_f32_16x16x32_bf16 v[72:75], v[198:201], v[250:253], v[72:75]
	v_mfma_f32_16x16x32_bf16 v[68:71], v[216:219], v[250:253], v[68:71]
	v_mfma_f32_16x16x32_bf16 v[64:67], v[220:223], v[250:253], v[64:67]
	ds_read_b128 v[246:249], v186 offset:6144
	ds_read_b128 v[250:253], v186 offset:7168
	s_waitcnt lgkmcnt(2)
	v_mfma_f32_16x16x32_bf16 v[60:63], v[194:197], v[202:205], v[60:63]
	v_lshl_add_u64 v[226:227], v[154:155], 0, s[12:13]
	v_mfma_f32_16x16x32_bf16 v[56:59], v[198:201], v[202:205], v[56:59]
	s_mov_b32 m0, s14
	v_mfma_f32_16x16x32_bf16 v[52:55], v[216:219], v[202:205], v[52:55]
	s_add_i32 s14, s14, 0x2000
	v_mfma_f32_16x16x32_bf16 v[48:51], v[220:223], v[202:205], v[48:51]
	global_load_lds_dwordx4 v[226:227], off
	v_mfma_f32_16x16x32_bf16 v[44:47], v[194:197], v[212:215], v[44:47]
	v_mfma_f32_16x16x32_bf16 v[40:43], v[198:201], v[212:215], v[40:43]
	v_mfma_f32_16x16x32_bf16 v[36:39], v[216:219], v[212:215], v[36:39]
	v_mfma_f32_16x16x32_bf16 v[32:35], v[220:223], v[212:215], v[32:35]
	s_add_i32 s7, s7, 0x8000
	s_and_b32 s7, s7, 0x18000
	s_waitcnt vmcnt(7) lgkmcnt(0)
	s_barrier
	v_add3_u32 v187, v181, v163, s7
	v_add3_u32 v186, v181, v164, s7
	s_nop 0
	ds_read_b128 v[230:233], v187 offset:16384
	ds_read_b128 v[234:237], v187 offset:17408
	ds_read_b128 v[238:241], v187 offset:18432
	ds_read_b128 v[242:245], v187 offset:19456
	ds_read_b128 v[202:205], v186
	ds_read_b128 v[212:215], v186 offset:1024
	v_mfma_f32_16x16x32_bf16 v[28:31], v[194:197], v[246:249], v[28:31]
	v_lshl_add_u64 v[228:229], v[156:157], 0, s[12:13]
	v_mfma_f32_16x16x32_bf16 v[24:27], v[198:201], v[246:249], v[24:27]
	s_mov_b32 m0, s14
	v_mfma_f32_16x16x32_bf16 v[20:23], v[216:219], v[246:249], v[20:23]
	s_add_i32 s14, s14, 0x2000
	v_mfma_f32_16x16x32_bf16 v[16:19], v[220:223], v[246:249], v[16:19]
	global_load_lds_dwordx4 v[228:229], off
	v_mfma_f32_16x16x32_bf16 v[12:15], v[194:197], v[250:253], v[12:15]
	s_add_u32 s12, s12, 64
	v_mfma_f32_16x16x32_bf16 v[8:11], v[198:201], v[250:253], v[8:11]
	s_addc_u32 s13, s13, 0
	v_mfma_f32_16x16x32_bf16 v[4:7], v[216:219], v[250:253], v[4:7]
	v_mfma_f32_16x16x32_bf16 v[0:3], v[220:223], v[250:253], v[0:3]
	s_add_i32 s9, s7, 0x18000
	s_and_b32 s9, s9, 0x18000
	s_add_i32 s14, s9, s11
	ds_read_b128 v[246:249], v186 offset:2048
	ds_read_b128 v[250:253], v186 offset:3072
	s_waitcnt lgkmcnt(2)
	v_mfma_f32_16x16x32_bf16 v[124:127], v[230:233], v[202:205], v[124:127]
	v_lshl_add_u64 v[206:207], v[158:159], 0, s[12:13]
	v_mfma_f32_16x16x32_bf16 v[120:123], v[234:237], v[202:205], v[120:123]
	s_mov_b32 m0, s14
	v_mfma_f32_16x16x32_bf16 v[116:119], v[238:241], v[202:205], v[116:119]
	s_add_i32 s14, s14, 0x2000
	v_mfma_f32_16x16x32_bf16 v[112:115], v[242:245], v[202:205], v[112:115]
	global_load_lds_dwordx4 v[206:207], off
	v_mfma_f32_16x16x32_bf16 v[108:111], v[230:233], v[212:215], v[108:111]
	v_mfma_f32_16x16x32_bf16 v[104:107], v[234:237], v[212:215], v[104:107]
	v_mfma_f32_16x16x32_bf16 v[100:103], v[238:241], v[212:215], v[100:103]
	v_mfma_f32_16x16x32_bf16 v[96:99], v[242:245], v[212:215], v[96:99]
	ds_read_b128 v[202:205], v186 offset:4096
	ds_read_b128 v[212:215], v186 offset:5120
	s_waitcnt lgkmcnt(2)
	v_mfma_f32_16x16x32_bf16 v[92:95], v[230:233], v[246:249], v[92:95]
	v_lshl_add_u64 v[224:225], v[160:161], 0, s[12:13]
	v_mfma_f32_16x16x32_bf16 v[88:91], v[234:237], v[246:249], v[88:91]
	s_mov_b32 m0, s14
	v_mfma_f32_16x16x32_bf16 v[84:87], v[238:241], v[246:249], v[84:87]
	s_add_i32 s14, s14, 0x2000
	v_mfma_f32_16x16x32_bf16 v[80:83], v[242:245], v[246:249], v[80:83]
	global_load_lds_dwordx4 v[224:225], off
	v_mfma_f32_16x16x32_bf16 v[76:79], v[230:233], v[250:253], v[76:79]
	v_mfma_f32_16x16x32_bf16 v[72:75], v[234:237], v[250:253], v[72:75]
	v_mfma_f32_16x16x32_bf16 v[68:71], v[238:241], v[250:253], v[68:71]
	v_mfma_f32_16x16x32_bf16 v[64:67], v[242:245], v[250:253], v[64:67]
	ds_read_b128 v[246:249], v186 offset:6144
	ds_read_b128 v[250:253], v186 offset:7168
	s_waitcnt lgkmcnt(2)
	v_mfma_f32_16x16x32_bf16 v[60:63], v[230:233], v[202:205], v[60:63]
	v_lshl_add_u64 v[226:227], v[154:155], 0, s[12:13]
	v_mfma_f32_16x16x32_bf16 v[56:59], v[234:237], v[202:205], v[56:59]
	s_mov_b32 m0, s14
	v_mfma_f32_16x16x32_bf16 v[52:55], v[238:241], v[202:205], v[52:55]
	s_add_i32 s14, s14, 0x2000
	v_mfma_f32_16x16x32_bf16 v[48:51], v[242:245], v[202:205], v[48:51]
	global_load_lds_dwordx4 v[226:227], off
	v_mfma_f32_16x16x32_bf16 v[44:47], v[230:233], v[212:215], v[44:47]
	v_mfma_f32_16x16x32_bf16 v[40:43], v[234:237], v[212:215], v[40:43]
	v_mfma_f32_16x16x32_bf16 v[36:39], v[238:241], v[212:215], v[36:39]
	v_mfma_f32_16x16x32_bf16 v[32:35], v[242:245], v[212:215], v[32:35]
	s_add_i32 s7, s7, 0x8000
	s_and_b32 s7, s7, 0x18000
	s_waitcnt vmcnt(7) lgkmcnt(0)
	s_barrier
; template <class Epi>
; DI void gemm_tile256(const u16* __restrict__ Ag, long lda, const u16* __restrict__ Bg, long ldb, int nk, char* shm, Epi&& epi) {
;     ...
;   for (int i = 0; i < nk; ++i) {
;     if (i + 2 < nk) asm volatile("s_waitcnt vmcnt(8)" ::: "memory");
;     else if (i + 1 < nk) asm volatile("s_waitcnt vmcnt(4)" ::: "memory");
;     else asm volatile("s_waitcnt vmcnt(0)" ::: "memory");
;     __builtin_amdgcn_s_barrier();
;     const char* SA = shm + (i & 3) * 32768; const char* SB = SA + 16384;
;     bf16x8 At[8], Bt[4];
; #pragma unroll
;     for (int n = 0; n < 4; ++n) { const int rb = wc * 64 + n * 16 + fr; Bt[n] = *reinterpret_cast<const bf16x8*>(SB + rb * 64 + ((fq ^ ((rb >> 2) & 3)) * 16)); }
; #pragma unroll
;     for (int m = 0; m < 8; ++m) { const int ra = wr * 128 + m * 16 + fr; At[m] = *reinterpret_cast<const bf16x8*>(SA + ra * 64 + ((fq ^ ((ra >> 2) & 3)) * 16)); }
;     if (i + 3 < nk) stage(i + 3);
; #pragma unroll
;     for (int m = 0; m < 8; ++m)
; #pragma unroll
;       for (int n = 0; n < 4; ++n) acc[m][n] = __builtin_amdgcn_mfma_f32_16x16x32_bf16(Bt[n], At[m], acc[m][n], 0, 0, 0);
;   }
	v_add3_u32 v187, v181, v163, s7
	v_add3_u32 v186, v181, v164, s7
	s_nop 0
	ds_read_b128 v[194:197], v187 offset:16384
	ds_read_b128 v[198:201], v187 offset:17408
	ds_read_b128 v[216:219], v187 offset:18432
	ds_read_b128 v[220:223], v187 offset:19456
	ds_read_b128 v[202:205], v186
	ds_read_b128 v[212:215], v186 offset:1024
	v_mfma_f32_16x16x32_bf16 v[28:31], v[230:233], v[246:249], v[28:31]
	v_lshl_add_u64 v[228:229], v[156:157], 0, s[12:13]
	v_mfma_f32_16x16x32_bf16 v[24:27], v[234:237], v[246:249], v[24:27]
	s_mov_b32 m0, s14
	v_mfma_f32_16x16x32_bf16 v[20:23], v[238:241], v[246:249], v[20:23]
	s_add_i32 s14, s14, 0x2000
	v_mfma_f32_16x16x32_bf16 v[16:19], v[242:245], v[246:249], v[16:19]
	global_load_lds_dwordx4 v[228:229], off
	v_mfma_f32_16x16x32_bf16 v[12:15], v[230:233], v[250:253], v[12:15]
	s_add_u32 s12, s12, 64
	v_mfma_f32_16x16x32_bf16 v[8:11], v[234:237], v[250:253], v[8:11]
	s_addc_u32 s13, s13, 0
	v_mfma_f32_16x16x32_bf16 v[4:7], v[238:241], v[250:253], v[4:7]
	v_mfma_f32_16x16x32_bf16 v[0:3], v[242:245], v[250:253], v[0:3]
	s_cmpk_lg_i32 s12, 0x700
	s_cbranch_scc1 .Lgemm_p8_kloop
	s_add_i32 s9, s7, 0x18000
	s_and_b32 s9, s9, 0x18000
	s_add_i32 s14, s9, s11
	ds_read_b128 v[246:249], v186 offset:2048
	ds_read_b128 v[250:253], v186 offset:3072
	s_waitcnt lgkmcnt(2)
	v_mfma_f32_16x16x32_bf16 v[124:127], v[194:197], v[202:205], v[124:127]
	v_lshl_add_u64 v[206:207], v[158:159], 0, s[12:13]
	v_mfma_f32_16x16x32_bf16 v[120:123], v[198:201], v[202:205], v[120:123]
	s_mov_b32 m0, s14
	v_mfma_f32_16x16x32_bf16 v[116:119], v[216:219], v[202:205], v[116:119]
	s_add_i32 s14, s14, 0x2000
	v_mfma_f32_16x16x32_bf16 v[112:115], v[220:223], v[202:205], v[112:115]
	global_load_lds_dwordx4 v[206:207], off
	v_mfma_f32_16x16x32_bf16 v[108:111], v[194:197], v[212:215], v[108:111]
	v_mfma_f32_16x16x32_bf16 v[104:107], v[198:201], v[212:215], v[104:107]
	v_mfma_f32_16x16x32_bf16 v[100:103], v[216:219], v[212:215], v[100:103]
	v_mfma_f32_16x16x32_bf16 v[96:99], v[220:223], v[212:215], v[96:99]
	ds_read_b128 v[202:205], v186 offset:4096
	ds_read_b128 v[212:215], v186 offset:5120
	s_waitcnt lgkmcnt(2)
	v_mfma_f32_16x16x32_bf16 v[92:95], v[194:197], v[246:249], v[92:95]
	v_lshl_add_u64 v[224:225], v[160:161], 0, s[12:13]
	v_mfma_f32_16x16x32_bf16 v[88:91], v[198:201], v[246:249], v[88:91]
	s_mov_b32 m0, s14
	v_mfma_f32_16x16x32_bf16 v[84:87], v[216:219], v[246:249], v[84:87]
	s_add_i32 s14, s14, 0x2000
	v_mfma_f32_16x16x32_bf16 v[80:83], v[220:223], v[246:249], v[80:83]
	global_load_lds_dwordx4 v[224:225], off
	v_mfma_f32_16x16x32_bf16 v[76:79], v[194:197], v[250:253], v[76:79]
	v_mfma_f32_16x16x32_bf16 v[72:75], v[198:201], v[250:253], v[72:75]
	v_mfma_f32_16x16x32_bf16 v[68:71], v[216:219], v[250:253], v[68:71]
	v_mfma_f32_16x16x32_bf16 v[64:67], v[220:223], v[250:253], v[64:67]
	ds_read_b128 v[246:249], v186 offset:6144
	ds_read_b128 v[250:253], v186 offset:7168
	s_waitcnt lgkmcnt(2)
	v_mfma_f32_16x16x32_bf16 v[60:63], v[194:197], v[202:205], v[60:63]
	v_lshl_add_u64 v[226:227], v[154:155], 0, s[12:13]
	v_mfma_f32_16x16x32_bf16 v[56:59], v[198:201], v[202:205], v[56:59]
	s_mov_b32 m0, s14
	v_mfma_f32_16x16x32_bf16 v[52:55], v[216:219], v[202:205], v[52:55]
	s_add_i32 s14, s14, 0x2000
	v_mfma_f32_16x16x32_bf16 v[48:51], v[220:223], v[202:205], v[48:51]
	global_load_lds_dwordx4 v[226:227], off
	v_mfma_f32_16x16x32_bf16 v[44:47], v[194:197], v[212:215], v[44:47]
	v_mfma_f32_16x16x32_bf16 v[40:43], v[198:201], v[212:215], v[40:43]
	v_mfma_f32_16x16x32_bf16 v[36:39], v[216:219], v[212:215], v[36:39]
	v_mfma_f32_16x16x32_bf16 v[32:35], v[220:223], v[212:215], v[32:35]
	s_add_i32 s7, s7, 0x8000
	s_and_b32 s7, s7, 0x18000
	s_waitcnt vmcnt(7) lgkmcnt(0)
	s_barrier
	v_add3_u32 v187, v181, v163, s7
	v_add3_u32 v186, v181, v164, s7
	s_nop 0
	ds_read_b128 v[230:233], v187 offset:16384
	ds_read_b128 v[234:237], v187 offset:17408
	ds_read_b128 v[238:241], v187 offset:18432
	ds_read_b128 v[242:245], v187 offset:19456
	ds_read_b128 v[202:205], v186
	ds_read_b128 v[212:215], v186 offset:1024
	v_mfma_f32_16x16x32_bf16 v[28:31], v[194:197], v[246:249], v[28:31]
	v_lshl_add_u64 v[228:229], v[156:157], 0, s[12:13]
	v_mfma_f32_16x16x32_bf16 v[24:27], v[198:201], v[246:249], v[24:27]
	s_mov_b32 m0, s14
	v_mfma_f32_16x16x32_bf16 v[20:23], v[216:219], v[246:249], v[20:23]
	s_add_i32 s14, s14, 0x2000
	v_mfma_f32_16x16x32_bf16 v[16:19], v[220:223], v[246:249], v[16:19]
	global_load_lds_dwordx4 v[228:229], off
	v_mfma_f32_16x16x32_bf16 v[12:15], v[194:197], v[250:253], v[12:15]
	s_add_u32 s12, s12, 64
	v_mfma_f32_16x16x32_bf16 v[8:11], v[198:201], v[250:253], v[8:11]
	s_addc_u32 s13, s13, 0
	v_mfma_f32_16x16x32_bf16 v[4:7], v[216:219], v[250:253], v[4:7]
	v_mfma_f32_16x16x32_bf16 v[0:3], v[220:223], v[250:253], v[0:3]
	ds_read_b128 v[246:249], v186 offset:2048
	ds_read_b128 v[250:253], v186 offset:3072
	s_waitcnt lgkmcnt(2)
	v_mfma_f32_16x16x32_bf16 v[124:127], v[230:233], v[202:205], v[124:127]
	v_mfma_f32_16x16x32_bf16 v[120:123], v[234:237], v[202:205], v[120:123]
	v_mfma_f32_16x16x32_bf16 v[116:119], v[238:241], v[202:205], v[116:119]
	v_mfma_f32_16x16x32_bf16 v[112:115], v[242:245], v[202:205], v[112:115]
	v_mfma_f32_16x16x32_bf16 v[108:111], v[230:233], v[212:215], v[108:111]
	v_mfma_f32_16x16x32_bf16 v[104:107], v[234:237], v[212:215], v[104:107]
	v_mfma_f32_16x16x32_bf16 v[100:103], v[238:241], v[212:215], v[100:103]
	v_mfma_f32_16x16x32_bf16 v[96:99], v[242:245], v[212:215], v[96:99]
	ds_read_b128 v[202:205], v186 offset:4096
	ds_read_b128 v[212:215], v186 offset:5120
	s_waitcnt lgkmcnt(2)
	v_mfma_f32_16x16x32_bf16 v[92:95], v[230:233], v[246:249], v[92:95]
	v_mfma_f32_16x16x32_bf16 v[88:91], v[234:237], v[246:249], v[88:91]
	v_mfma_f32_16x16x32_bf16 v[84:87], v[238:241], v[246:249], v[84:87]
	v_mfma_f32_16x16x32_bf16 v[80:83], v[242:245], v[246:249], v[80:83]
	v_mfma_f32_16x16x32_bf16 v[76:79], v[230:233], v[250:253], v[76:79]
	v_mfma_f32_16x16x32_bf16 v[72:75], v[234:237], v[250:253], v[72:75]
	v_mfma_f32_16x16x32_bf16 v[68:71], v[238:241], v[250:253], v[68:71]
	v_mfma_f32_16x16x32_bf16 v[64:67], v[242:245], v[250:253], v[64:67]
	ds_read_b128 v[246:249], v186 offset:6144
	ds_read_b128 v[250:253], v186 offset:7168
	s_waitcnt lgkmcnt(2)
	v_mfma_f32_16x16x32_bf16 v[60:63], v[230:233], v[202:205], v[60:63]
	v_mfma_f32_16x16x32_bf16 v[56:59], v[234:237], v[202:205], v[56:59]
	v_mfma_f32_16x16x32_bf16 v[52:55], v[238:241], v[202:205], v[52:55]
	v_mfma_f32_16x16x32_bf16 v[48:51], v[242:245], v[202:205], v[48:51]
	v_mfma_f32_16x16x32_bf16 v[44:47], v[230:233], v[212:215], v[44:47]
	v_mfma_f32_16x16x32_bf16 v[40:43], v[234:237], v[212:215], v[40:43]
	v_mfma_f32_16x16x32_bf16 v[36:39], v[238:241], v[212:215], v[36:39]
	v_mfma_f32_16x16x32_bf16 v[32:35], v[242:245], v[212:215], v[32:35]
	s_add_i32 s7, s7, 0x8000
	s_and_b32 s7, s7, 0x18000
	s_waitcnt vmcnt(4) lgkmcnt(0)
	s_barrier
; template <class Epi>
; DI void gemm_tile256(const u16* __restrict__ Ag, long lda, const u16* __restrict__ Bg, long ldb, int nk, char* shm, Epi&& epi) {
;     ...
;   for (int i = 0; i < nk; ++i) {
;     if (i + 2 < nk) asm volatile("s_waitcnt vmcnt(8)" ::: "memory");
;     else if (i + 1 < nk) asm volatile("s_waitcnt vmcnt(4)" ::: "memory");
;     else asm volatile("s_waitcnt vmcnt(0)" ::: "memory");
;     __builtin_amdgcn_s_barrier();
;     const char* SA = shm + (i & 3) * 32768; const char* SB = SA + 16384;
;     bf16x8 At[8], Bt[4];
; #pragma unroll
;     for (int n = 0; n < 4; ++n) { const int rb = wc * 64 + n * 16 + fr; Bt[n] = *reinterpret_cast<const bf16x8*>(SB + rb * 64 + ((fq ^ ((rb >> 2) & 3)) * 16)); }
; #pragma unroll
;     for (int m = 0; m < 8; ++m) { const int ra = wr * 128 + m * 16 + fr; At[m] = *reinterpret_cast<const bf16x8*>(SA + ra * 64 + ((fq ^ ((ra >> 2) & 3)) * 16)); }
;     if (i + 3 < nk) stage(i + 3);
; #pragma unroll
;     for (int m = 0; m < 8; ++m)
; #pragma unroll
;       for (int n = 0; n < 4; ++n) acc[m][n] = __builtin_amdgcn_mfma_f32_16x16x32_bf16(Bt[n], At[m], acc[m][n], 0, 0, 0);
;   }
;   __syncthreads();
	v_add3_u32 v187, v181, v163, s7
	v_add3_u32 v186, v181, v164, s7
	s_nop 0
	ds_read_b128 v[194:197], v187 offset:16384
	ds_read_b128 v[198:201], v187 offset:17408
	ds_read_b128 v[216:219], v187 offset:18432
	ds_read_b128 v[220:223], v187 offset:19456
	ds_read_b128 v[202:205], v186
	ds_read_b128 v[212:215], v186 offset:1024
	v_mfma_f32_16x16x32_bf16 v[28:31], v[230:233], v[246:249], v[28:31]
	v_mfma_f32_16x16x32_bf16 v[24:27], v[234:237], v[246:249], v[24:27]
	v_mfma_f32_16x16x32_bf16 v[20:23], v[238:241], v[246:249], v[20:23]
	v_mfma_f32_16x16x32_bf16 v[16:19], v[242:245], v[246:249], v[16:19]
	v_mfma_f32_16x16x32_bf16 v[12:15], v[230:233], v[250:253], v[12:15]
	v_mfma_f32_16x16x32_bf16 v[8:11], v[234:237], v[250:253], v[8:11]
	v_mfma_f32_16x16x32_bf16 v[4:7], v[238:241], v[250:253], v[4:7]
	v_mfma_f32_16x16x32_bf16 v[0:3], v[242:245], v[250:253], v[0:3]
	ds_read_b128 v[246:249], v186 offset:2048
	ds_read_b128 v[250:253], v186 offset:3072
	s_waitcnt lgkmcnt(2)
	v_mfma_f32_16x16x32_bf16 v[124:127], v[194:197], v[202:205], v[124:127]
	v_mfma_f32_16x16x32_bf16 v[120:123], v[198:201], v[202:205], v[120:123]
	v_mfma_f32_16x16x32_bf16 v[116:119], v[216:219], v[202:205], v[116:119]
	v_mfma_f32_16x16x32_bf16 v[112:115], v[220:223], v[202:205], v[112:115]
	v_mfma_f32_16x16x32_bf16 v[108:111], v[194:197], v[212:215], v[108:111]
	v_mfma_f32_16x16x32_bf16 v[104:107], v[198:201], v[212:215], v[104:107]
	v_mfma_f32_16x16x32_bf16 v[100:103], v[216:219], v[212:215], v[100:103]
	v_mfma_f32_16x16x32_bf16 v[96:99], v[220:223], v[212:215], v[96:99]
	ds_read_b128 v[202:205], v186 offset:4096
	ds_read_b128 v[212:215], v186 offset:5120
	s_waitcnt lgkmcnt(2)
	v_mfma_f32_16x16x32_bf16 v[92:95], v[194:197], v[246:249], v[92:95]
	v_mfma_f32_16x16x32_bf16 v[88:91], v[198:201], v[246:249], v[88:91]
	v_mfma_f32_16x16x32_bf16 v[84:87], v[216:219], v[246:249], v[84:87]
	v_mfma_f32_16x16x32_bf16 v[80:83], v[220:223], v[246:249], v[80:83]
	v_mfma_f32_16x16x32_bf16 v[76:79], v[194:197], v[250:253], v[76:79]
	v_mfma_f32_16x16x32_bf16 v[72:75], v[198:201], v[250:253], v[72:75]
	v_mfma_f32_16x16x32_bf16 v[68:71], v[216:219], v[250:253], v[68:71]
	v_mfma_f32_16x16x32_bf16 v[64:67], v[220:223], v[250:253], v[64:67]
	ds_read_b128 v[246:249], v186 offset:6144
	ds_read_b128 v[250:253], v186 offset:7168
	s_waitcnt lgkmcnt(2)
	v_mfma_f32_16x16x32_bf16 v[60:63], v[194:197], v[202:205], v[60:63]
	v_mfma_f32_16x16x32_bf16 v[56:59], v[198:201], v[202:205], v[56:59]
	v_mfma_f32_16x16x32_bf16 v[52:55], v[216:219], v[202:205], v[52:55]
	v_mfma_f32_16x16x32_bf16 v[48:51], v[220:223], v[202:205], v[48:51]
	v_mfma_f32_16x16x32_bf16 v[44:47], v[194:197], v[212:215], v[44:47]
	v_mfma_f32_16x16x32_bf16 v[40:43], v[198:201], v[212:215], v[40:43]
	v_mfma_f32_16x16x32_bf16 v[36:39], v[216:219], v[212:215], v[36:39]
	v_mfma_f32_16x16x32_bf16 v[32:35], v[220:223], v[212:215], v[32:35]
	s_add_i32 s7, s7, 0x8000
	s_and_b32 s7, s7, 0x18000
	s_waitcnt vmcnt(0) lgkmcnt(0)
	s_barrier
	v_add3_u32 v187, v181, v163, s7
	v_add3_u32 v186, v181, v164, s7
	s_nop 0
	ds_read_b128 v[230:233], v187 offset:16384
	ds_read_b128 v[234:237], v187 offset:17408
	ds_read_b128 v[238:241], v187 offset:18432
	ds_read_b128 v[242:245], v187 offset:19456
	ds_read_b128 v[202:205], v186
	ds_read_b128 v[212:215], v186 offset:1024
	v_mfma_f32_16x16x32_bf16 v[28:31], v[194:197], v[246:249], v[28:31]
	v_mfma_f32_16x16x32_bf16 v[24:27], v[198:201], v[246:249], v[24:27]
	v_mfma_f32_16x16x32_bf16 v[20:23], v[216:219], v[246:249], v[20:23]
	v_mfma_f32_16x16x32_bf16 v[16:19], v[220:223], v[246:249], v[16:19]
	v_mfma_f32_16x16x32_bf16 v[12:15], v[194:197], v[250:253], v[12:15]
	v_mfma_f32_16x16x32_bf16 v[8:11], v[198:201], v[250:253], v[8:11]
	v_mfma_f32_16x16x32_bf16 v[4:7], v[216:219], v[250:253], v[4:7]
	v_mfma_f32_16x16x32_bf16 v[0:3], v[220:223], v[250:253], v[0:3]
	ds_read_b128 v[246:249], v186 offset:2048
	ds_read_b128 v[250:253], v186 offset:3072
	s_waitcnt lgkmcnt(2)
	v_mfma_f32_16x16x32_bf16 v[124:127], v[230:233], v[202:205], v[124:127]
	v_mfma_f32_16x16x32_bf16 v[120:123], v[234:237], v[202:205], v[120:123]
	v_mfma_f32_16x16x32_bf16 v[116:119], v[238:241], v[202:205], v[116:119]
	v_mfma_f32_16x16x32_bf16 v[112:115], v[242:245], v[202:205], v[112:115]
	v_mfma_f32_16x16x32_bf16 v[108:111], v[230:233], v[212:215], v[108:111]
	v_mfma_f32_16x16x32_bf16 v[104:107], v[234:237], v[212:215], v[104:107]
	v_mfma_f32_16x16x32_bf16 v[100:103], v[238:241], v[212:215], v[100:103]
	v_mfma_f32_16x16x32_bf16 v[96:99], v[242:245], v[212:215], v[96:99]
	ds_read_b128 v[202:205], v186 offset:4096
	ds_read_b128 v[212:215], v186 offset:5120
	s_waitcnt lgkmcnt(2)
	v_mfma_f32_16x16x32_bf16 v[92:95], v[230:233], v[246:249], v[92:95]
	v_mfma_f32_16x16x32_bf16 v[88:91], v[234:237], v[246:249], v[88:91]
	v_mfma_f32_16x16x32_bf16 v[84:87], v[238:241], v[246:249], v[84:87]
	v_mfma_f32_16x16x32_bf16 v[80:83], v[242:245], v[246:249], v[80:83]
	v_mfma_f32_16x16x32_bf16 v[76:79], v[230:233], v[250:253], v[76:79]
	v_mfma_f32_16x16x32_bf16 v[72:75], v[234:237], v[250:253], v[72:75]
	v_mfma_f32_16x16x32_bf16 v[68:71], v[238:241], v[250:253], v[68:71]
	v_mfma_f32_16x16x32_bf16 v[64:67], v[242:245], v[250:253], v[64:67]
	ds_read_b128 v[246:249], v186 offset:6144
	ds_read_b128 v[250:253], v186 offset:7168
	s_waitcnt lgkmcnt(2)
	v_mfma_f32_16x16x32_bf16 v[60:63], v[230:233], v[202:205], v[60:63]
	v_mfma_f32_16x16x32_bf16 v[56:59], v[234:237], v[202:205], v[56:59]
	v_mfma_f32_16x16x32_bf16 v[52:55], v[238:241], v[202:205], v[52:55]
	v_mfma_f32_16x16x32_bf16 v[48:51], v[242:245], v[202:205], v[48:51]
	v_mfma_f32_16x16x32_bf16 v[44:47], v[230:233], v[212:215], v[44:47]
	v_mfma_f32_16x16x32_bf16 v[40:43], v[234:237], v[212:215], v[40:43]
	v_mfma_f32_16x16x32_bf16 v[36:39], v[238:241], v[212:215], v[36:39]
	v_mfma_f32_16x16x32_bf16 v[32:35], v[242:245], v[212:215], v[32:35]
	s_waitcnt lgkmcnt(0)
	v_mfma_f32_16x16x32_bf16 v[28:31], v[230:233], v[246:249], v[28:31]
	v_mfma_f32_16x16x32_bf16 v[24:27], v[234:237], v[246:249], v[24:27]
	v_mfma_f32_16x16x32_bf16 v[20:23], v[238:241], v[246:249], v[20:23]
	v_mfma_f32_16x16x32_bf16 v[16:19], v[242:245], v[246:249], v[16:19]
	v_mfma_f32_16x16x32_bf16 v[12:15], v[230:233], v[250:253], v[12:15]
	v_mfma_f32_16x16x32_bf16 v[8:11], v[234:237], v[250:253], v[8:11]
	v_mfma_f32_16x16x32_bf16 v[4:7], v[238:241], v[250:253], v[4:7]
	v_mfma_f32_16x16x32_bf16 v[0:3], v[242:245], v[250:253], v[0:3]
	s_nop 7
	s_nop 3
	s_add_i32 s75, s75, s5
	s_add_i32 s6, s6, s8
	s_cmpk_lt_i32 s75, 0x80
	s_waitcnt vmcnt(0) lgkmcnt(0)
	s_barrier
; DI unsigned pack2bf(float a, float b) { const f2_t v = {a, b}; return __builtin_bit_cast(unsigned, __builtin_convertvector(v, bf2_t)); }
; template <class Epi>
; DI void gemm_tile256(const u16* __restrict__ Ag, long lda, const u16* __restrict__ Bg, long ldb, int nk, char* shm, Epi&& epi) {
;     ...
;   for (int m = 0; m < 8; ++m)
; #pragma unroll
;     for (int n = 0; n < 4; ++n) epi(wr * 128 + m * 16 + fr, wc * 64 + n * 16 + fq * 4, acc[m][n]);
; DI void phase8(const Params& P, char* smem) {
;     ...
;     gemm_tile256(h1b + (long)brow * 1024, 1024, WqT + (long)bcol * 1024, 1024, 32, smem, [&](int row, int col0, f32x4 v) {
;       *reinterpret_cast<uint2*>(Qp + (long)(brow + row) * 2048 + bcol + col0) = make_uint2(pack2bf(v[0], v[1]), pack2bf(v[2], v[3]));
;     });
	s_nop 6
	v_cvt_pk_bf16_f32 v124, v124, v125
	v_cvt_pk_bf16_f32 v125, v126, v127
	v_add_u32_e32 v126, s10, v165
	v_ashrrev_i32_e32 v127, 31, v126
	v_cvt_pk_bf16_f32 v108, v108, v109
	v_cvt_pk_bf16_f32 v109, v110, v111
	v_add_u32_e32 v110, s10, v166
	s_nop 2
	v_cvt_pk_bf16_f32 v92, v92, v93
	v_cvt_pk_bf16_f32 v93, v94, v95
	v_add_u32_e32 v94, s10, v167
	v_cvt_pk_bf16_f32 v76, v76, v77
	v_cvt_pk_bf16_f32 v77, v78, v79
	v_add_u32_e32 v78, s10, v176
	s_nop 2
	v_cvt_pk_bf16_f32 v60, v60, v61
	v_cvt_pk_bf16_f32 v61, v62, v63
	v_add_u32_e32 v62, s10, v177
	v_cvt_pk_bf16_f32 v44, v44, v45
	v_cvt_pk_bf16_f32 v45, v46, v47
	v_add_u32_e32 v46, s10, v178
	s_nop 2
	v_cvt_pk_bf16_f32 v28, v28, v29
	v_cvt_pk_bf16_f32 v29, v30, v31
	v_add_u32_e32 v30, s10, v179
	v_cvt_pk_bf16_f32 v12, v12, v13
	v_cvt_pk_bf16_f32 v13, v14, v15
	v_add_u32_e32 v14, s10, v180
	v_ashrrev_i32_e32 v111, 31, v110
	v_ashrrev_i32_e32 v95, 31, v94
	v_ashrrev_i32_e32 v79, 31, v78
	v_ashrrev_i32_e32 v63, 31, v62
	v_ashrrev_i32_e32 v47, 31, v46
	v_ashrrev_i32_e32 v31, 31, v30
	v_ashrrev_i32_e32 v15, 31, v14
	v_lshlrev_b64 v[126:127], 12, v[126:127]
	v_lshlrev_b64 v[110:111], 12, v[110:111]
	v_lshlrev_b64 v[94:95], 12, v[94:95]
	v_lshlrev_b64 v[78:79], 12, v[78:79]
	v_lshlrev_b64 v[62:63], 12, v[62:63]
	v_lshlrev_b64 v[46:47], 12, v[46:47]
	v_lshlrev_b64 v[30:31], 12, v[30:31]
	v_lshlrev_b64 v[14:15], 12, v[14:15]
	v_lshl_add_u64 v[126:127], v[148:149], 0, v[126:127]
	v_cvt_pk_bf16_f32 v120, v120, v121
	v_cvt_pk_bf16_f32 v121, v122, v123
	v_cvt_pk_bf16_f32 v116, v116, v117
	v_cvt_pk_bf16_f32 v117, v118, v119
	v_cvt_pk_bf16_f32 v112, v112, v113
	v_cvt_pk_bf16_f32 v113, v114, v115
	v_lshl_add_u64 v[110:111], v[148:149], 0, v[110:111]
	v_cvt_pk_bf16_f32 v104, v104, v105
	v_cvt_pk_bf16_f32 v105, v106, v107
	v_cvt_pk_bf16_f32 v100, v100, v101
	v_cvt_pk_bf16_f32 v101, v102, v103
	v_cvt_pk_bf16_f32 v96, v96, v97
	v_cvt_pk_bf16_f32 v97, v98, v99
	v_lshl_add_u64 v[94:95], v[148:149], 0, v[94:95]
	v_cvt_pk_bf16_f32 v88, v88, v89
	v_cvt_pk_bf16_f32 v89, v90, v91
	v_cvt_pk_bf16_f32 v84, v84, v85
	v_cvt_pk_bf16_f32 v85, v86, v87
	v_cvt_pk_bf16_f32 v80, v80, v81
	v_cvt_pk_bf16_f32 v81, v82, v83
	v_lshl_add_u64 v[78:79], v[148:149], 0, v[78:79]
	v_cvt_pk_bf16_f32 v72, v72, v73
	v_cvt_pk_bf16_f32 v73, v74, v75
	v_cvt_pk_bf16_f32 v68, v68, v69
	v_cvt_pk_bf16_f32 v69, v70, v71
	v_cvt_pk_bf16_f32 v64, v64, v65
	v_cvt_pk_bf16_f32 v65, v66, v67
	v_lshl_add_u64 v[62:63], v[148:149], 0, v[62:63]
	v_cvt_pk_bf16_f32 v56, v56, v57
	v_cvt_pk_bf16_f32 v57, v58, v59
	v_cvt_pk_bf16_f32 v52, v52, v53
	v_cvt_pk_bf16_f32 v53, v54, v55
	v_cvt_pk_bf16_f32 v48, v48, v49
	v_cvt_pk_bf16_f32 v49, v50, v51
	v_lshl_add_u64 v[46:47], v[148:149], 0, v[46:47]
	v_cvt_pk_bf16_f32 v40, v40, v41
	v_cvt_pk_bf16_f32 v41, v42, v43
	v_cvt_pk_bf16_f32 v36, v36, v37
	v_cvt_pk_bf16_f32 v37, v38, v39
	v_cvt_pk_bf16_f32 v32, v32, v33
	v_cvt_pk_bf16_f32 v33, v34, v35
	v_lshl_add_u64 v[30:31], v[148:149], 0, v[30:31]
	v_cvt_pk_bf16_f32 v24, v24, v25
	v_cvt_pk_bf16_f32 v25, v26, v27
	v_cvt_pk_bf16_f32 v20, v20, v21
	v_cvt_pk_bf16_f32 v21, v22, v23
	v_cvt_pk_bf16_f32 v16, v16, v17
	v_cvt_pk_bf16_f32 v17, v18, v19
	v_lshl_add_u64 v[14:15], v[148:149], 0, v[14:15]
	v_cvt_pk_bf16_f32 v8, v8, v9
	v_cvt_pk_bf16_f32 v9, v10, v11
	s_nop 1
	v_cvt_pk_bf16_f32 v4, v4, v5
	v_cvt_pk_bf16_f32 v5, v6, v7
	global_store_dwordx2 v[126:127], v[124:125], off
	s_nop 0
	v_cvt_pk_bf16_f32 v0, v0, v1
	v_cvt_pk_bf16_f32 v1, v2, v3
	global_store_dwordx2 v[126:127], v[120:121], off offset:32
	global_store_dwordx2 v[126:127], v[116:117], off offset:64
	global_store_dwordx2 v[126:127], v[112:113], off offset:96
	global_store_dwordx2 v[110:111], v[108:109], off
	global_store_dwordx2 v[110:111], v[104:105], off offset:32
	global_store_dwordx2 v[110:111], v[100:101], off offset:64
	global_store_dwordx2 v[110:111], v[96:97], off offset:96
	global_store_dwordx2 v[94:95], v[92:93], off
	global_store_dwordx2 v[94:95], v[88:89], off offset:32
	global_store_dwordx2 v[94:95], v[84:85], off offset:64
	global_store_dwordx2 v[94:95], v[80:81], off offset:96
	global_store_dwordx2 v[78:79], v[76:77], off
	global_store_dwordx2 v[78:79], v[72:73], off offset:32
	global_store_dwordx2 v[78:79], v[68:69], off offset:64
	global_store_dwordx2 v[78:79], v[64:65], off offset:96
	global_store_dwordx2 v[62:63], v[60:61], off
	global_store_dwordx2 v[62:63], v[56:57], off offset:32
	global_store_dwordx2 v[62:63], v[52:53], off offset:64
	global_store_dwordx2 v[62:63], v[48:49], off offset:96
	global_store_dwordx2 v[46:47], v[44:45], off
	global_store_dwordx2 v[46:47], v[40:41], off offset:32
	global_store_dwordx2 v[46:47], v[36:37], off offset:64
	global_store_dwordx2 v[46:47], v[32:33], off offset:96
	global_store_dwordx2 v[30:31], v[28:29], off
	global_store_dwordx2 v[30:31], v[24:25], off offset:32
	global_store_dwordx2 v[30:31], v[20:21], off offset:64
	global_store_dwordx2 v[30:31], v[16:17], off offset:96
	global_store_dwordx2 v[14:15], v[12:13], off
	global_store_dwordx2 v[14:15], v[8:9], off offset:32
	global_store_dwordx2 v[14:15], v[4:5], off offset:64
	global_store_dwordx2 v[14:15], v[0:1], off offset:96
	s_cbranch_scc1 .LBB0_1068
